# hand-written conv-mixer + weight conversion of layers 1-3 moved into idle last-round GEMM slots (phase 0 only for layer 0)
# speedup vs baseline: 1.0355x; 1.0145x over previous
; __device__ __forceinline__ int ltid() { int t = threadIdx.x; asm volatile("" : "+v"(t)); return t; }
; __device__ __forceinline__ int lbid() { int t = blockIdx.x; asm volatile("" : "+s"(t)); return t; }
; __device__ __forceinline__ void conv_mixer_rows(CArgs a, int layer, int G) {
;     const int lane = ltid() & 63, wave = ltid() >> 6;
;     const int gw = lbid() * NWAVES + wave, NGW = G * NWAVES;
;     const unsigned char* WSB = a->ws;
;     const bf16_t* U = (const bf16_t*)(a->ws + WS_U); bf16_t* Y = (bf16_t*)(a->ws + WS_Y);
;     const float* cw = a->conv_w + (size_t)layer * 3 * 512;
;     const int c0 = lane * 8;
;     float w[3][8];
; #pragma unroll
;     for (int k = 0; k < 3; ++k) { const f32x4 a0 = *(const f32x4*)(cw + k * 512 + c0), a1 = *(const f32x4*)(cw + k * 512 + c0 + 4);
;         w[k][0] = a0[0]; w[k][1] = a0[1]; w[k][2] = a0[2]; w[k][3] = a0[3]; w[k][4] = a1[0]; w[k][5] = a1[1]; w[k][6] = a1[2]; w[k][7] = a1[3]; }
;     auto load = [&](int row, u32x4 (&raw)[7]) {
;         const int s = row & (SEQ - 1);
; #pragma unroll
;         for (int k = 0; k < 3; ++k) {
;             const int sp = s + k - 1; const int rr = (sp >= 0 && sp < SEQ) ? row + k - 1 : row;
;             const bf16_t* ur = U + (size_t)rr * NU;
;             u32x4 h = *(const u32x4*)(ur + UCH + c0), c = *(const u32x4*)(ur + UCC + c0);
;             if (!(sp >= 0 && sp < SEQ)) { h = (u32x4){0u, 0u, 0u, 0u}; c = (u32x4){0u, 0u, 0u, 0u}; }
;             raw[2 * k] = h; raw[2 * k + 1] = c;
;         }
;         raw[6] = *(const u32x4*)(U + (size_t)row * NU + UCB + c0);
;     };
;     auto finish = [&](int row, const u32x4 (&raw)[7]) {
;         float accv[8];
; #pragma unroll
;         for (int e = 0; e < 8; ++e) accv[e] = 0.f;
; #pragma unroll
;         for (int k = 0; k < 3; ++k) { float ch[8], cc[8]; unpack8(raw[2 * k], ch); unpack8(raw[2 * k + 1], cc);
; #pragma unroll
;             for (int e = 0; e < 8; ++e) accv[e] += w[k][e] * (cc[e] * ch[e]); }
.Lp4_conv_entry:
	s_load_dwordx2 s[60:61], s[6:7], 0xe8
	s_load_dwordx2 s[12:13], s[6:7], 0xa8
	v_readfirstlane_b32 s10, v244
	v_and_b32_e32 v2, 63, v244
	v_lshlrev_b32_e32 v6, 5, v2
	v_lshlrev_b32_e32 v2, 4, v2
	v_add_u32_e32 v3, 0x2000, v2
	v_add_u32_e32 v4, 0x1c00, v2
	v_add_u32_e32 v5, 0xc00, v2
	v_add_u32_e32 v2, 0x1800, v2
	v_readlane_b32 s17, v253, 0
	s_lshr_b32 s10, s10, 6
	s_nop 3
	s_lshl_b32 s17, s17, 3
	s_add_i32 s10, s10, s17
	s_lshl_b32 s16, s64, 3
	s_mul_i32 s17, s8, 0x1800
	s_waitcnt lgkmcnt(0)
	s_and_b32 s61, s61, 0xffff
	s_add_u32 s12, s12, s17
	s_addc_u32 s13, s13, 0
	s_cmp_lt_u32 s10, 0x4000
	s_cbranch_scc0 .Lcvm_done
	global_load_dwordx4 v[8:11], v6, s[12:13]
	global_load_dwordx4 v[12:15], v6, s[12:13] offset:16
	global_load_dwordx4 v[16:19], v6, s[12:13] offset:2048
	global_load_dwordx4 v[20:23], v6, s[12:13] offset:2064
	s_add_u32 s12, s12, 0x1000
	s_addc_u32 s13, s13, 0
	global_load_dwordx4 v[24:27], v6, s[12:13]
	global_load_dwordx4 v[28:31], v6, s[12:13] offset:16
	s_and_b32 s21, s10, 0x7ff
	s_mul_i32 s19, s10, 0x2400
	s_add_u32 s19, s19, 0x3a00000
	s_sub_u32 s18, s19, 0x2400
	s_add_u32 s20, s19, 0x2400
	s_cmp_eq_u32 s21, 0
	s_cselect_b32 s18, s19, s18
	s_cmpk_eq_u32 s21, 0x7ff
	s_cselect_b32 s20, s19, s20
	buffer_load_dwordx4 v[32:35], v2, s[60:63], s18 offen
	buffer_load_dwordx4 v[36:39], v3, s[60:63], s18 offen
	buffer_load_dwordx4 v[40:43], v2, s[60:63], s19 offen
	buffer_load_dwordx4 v[44:47], v3, s[60:63], s19 offen
	buffer_load_dwordx4 v[48:51], v4, s[60:63], s19 offen
	buffer_load_dwordx4 v[52:55], v2, s[60:63], s20 offen
	buffer_load_dwordx4 v[56:59], v3, s[60:63], s20 offen
	s_mul_i32 s17, s16, 1
	s_add_i32 s17, s10, s17
	s_cmp_lt_u32 s17, 0x4000
	s_cselect_b32 s17, s17, s10
	s_and_b32 s21, s17, 0x7ff
	s_mul_i32 s19, s17, 0x2400
	s_add_u32 s19, s19, 0x3a00000
	s_sub_u32 s18, s19, 0x2400
	s_add_u32 s20, s19, 0x2400
	s_cmp_eq_u32 s21, 0
	s_cselect_b32 s18, s19, s18
	s_cmpk_eq_u32 s21, 0x7ff
	s_cselect_b32 s20, s19, s20
	buffer_load_dwordx4 v[60:63], v2, s[60:63], s18 offen
	buffer_load_dwordx4 v[64:67], v3, s[60:63], s18 offen
	buffer_load_dwordx4 v[68:71], v2, s[60:63], s19 offen
	buffer_load_dwordx4 v[72:75], v3, s[60:63], s19 offen
	buffer_load_dwordx4 v[76:79], v4, s[60:63], s19 offen
	buffer_load_dwordx4 v[80:83], v2, s[60:63], s20 offen
	buffer_load_dwordx4 v[84:87], v3, s[60:63], s20 offen
	s_mul_i32 s17, s16, 2
	s_add_i32 s17, s10, s17
	s_cmp_lt_u32 s17, 0x4000
	s_cselect_b32 s17, s17, s10
	s_and_b32 s21, s17, 0x7ff
	s_mul_i32 s19, s17, 0x2400
	s_add_u32 s19, s19, 0x3a00000
	s_sub_u32 s18, s19, 0x2400
	s_add_u32 s20, s19, 0x2400
	s_cmp_eq_u32 s21, 0
	s_cselect_b32 s18, s19, s18
	s_cmpk_eq_u32 s21, 0x7ff
	s_cselect_b32 s20, s19, s20
	buffer_load_dwordx4 v[88:91], v2, s[60:63], s18 offen
	buffer_load_dwordx4 v[92:95], v3, s[60:63], s18 offen
	buffer_load_dwordx4 v[96:99], v2, s[60:63], s19 offen
	buffer_load_dwordx4 v[100:103], v3, s[60:63], s19 offen
	buffer_load_dwordx4 v[104:107], v4, s[60:63], s19 offen
	buffer_load_dwordx4 v[108:111], v2, s[60:63], s20 offen
	buffer_load_dwordx4 v[112:115], v3, s[60:63], s20 offen
	s_waitcnt vmcnt(14)
	s_and_b32 s21, s10, 0x7ff
	s_cmp_lg_u32 s21, 0
	s_cbranch_scc1 .Lcvm_nz0_1
	v_mov_b32_e32 v32, 0
	v_mov_b32_e32 v33, 0
	v_mov_b32_e32 v34, 0
	v_mov_b32_e32 v35, 0
.Lcvm_nz0_1:
	s_cmpk_lg_u32 s21, 0x7ff
	s_cbranch_scc1 .Lcvm_nz2_1
	v_mov_b32_e32 v52, 0
	v_mov_b32_e32 v53, 0
	v_mov_b32_e32 v54, 0
	v_mov_b32_e32 v55, 0
.Lcvm_nz2_1:
	v_lshlrev_b32_e32 v128, 16, v32
	v_and_b32_e32 v129, 0xffff0000, v32
	v_lshlrev_b32_e32 v130, 16, v33
	v_and_b32_e32 v131, 0xffff0000, v33
	v_lshlrev_b32_e32 v132, 16, v34
	v_and_b32_e32 v133, 0xffff0000, v34
	v_lshlrev_b32_e32 v134, 16, v35
	v_and_b32_e32 v135, 0xffff0000, v35
	v_lshlrev_b32_e32 v136, 16, v36
	v_and_b32_e32 v137, 0xffff0000, v36
	v_lshlrev_b32_e32 v138, 16, v37
	v_and_b32_e32 v139, 0xffff0000, v37
	v_lshlrev_b32_e32 v140, 16, v38
	v_and_b32_e32 v141, 0xffff0000, v38
	v_lshlrev_b32_e32 v142, 16, v39
	v_and_b32_e32 v143, 0xffff0000, v39
	v_mul_f32_e32 v128, v136, v128
	v_mul_f32_e32 v129, v137, v129
	v_mul_f32_e32 v130, v138, v130
	v_mul_f32_e32 v131, v139, v131
	v_mul_f32_e32 v132, v140, v132
	v_mul_f32_e32 v133, v141, v133
	v_mul_f32_e32 v134, v142, v134
	v_mul_f32_e32 v135, v143, v135
	v_mul_f32_e32 v120, v8, v128
	v_mul_f32_e32 v121, v9, v129
	v_mul_f32_e32 v122, v10, v130
	v_mul_f32_e32 v123, v11, v131
	v_mul_f32_e32 v124, v12, v132
	v_mul_f32_e32 v125, v13, v133
	v_mul_f32_e32 v126, v14, v134
	v_mul_f32_e32 v127, v15, v135
	v_lshlrev_b32_e32 v128, 16, v40
	v_and_b32_e32 v129, 0xffff0000, v40
	v_lshlrev_b32_e32 v130, 16, v41
	v_and_b32_e32 v131, 0xffff0000, v41
	v_lshlrev_b32_e32 v132, 16, v42
	v_and_b32_e32 v133, 0xffff0000, v42
	v_lshlrev_b32_e32 v134, 16, v43
	v_and_b32_e32 v135, 0xffff0000, v43
	v_lshlrev_b32_e32 v136, 16, v44
	v_and_b32_e32 v137, 0xffff0000, v44
	v_lshlrev_b32_e32 v138, 16, v45
	v_and_b32_e32 v139, 0xffff0000, v45
	v_lshlrev_b32_e32 v140, 16, v46
	v_and_b32_e32 v141, 0xffff0000, v46
	v_lshlrev_b32_e32 v142, 16, v47
	v_and_b32_e32 v143, 0xffff0000, v47
	v_mul_f32_e32 v128, v136, v128
	v_mul_f32_e32 v129, v137, v129
	v_mul_f32_e32 v130, v138, v130
	v_mul_f32_e32 v131, v139, v131
	v_mul_f32_e32 v132, v140, v132
	v_mul_f32_e32 v133, v141, v133
	v_mul_f32_e32 v134, v142, v134
	v_mul_f32_e32 v135, v143, v135
	v_fmac_f32_e32 v120, v16, v128
	v_fmac_f32_e32 v121, v17, v129
	v_fmac_f32_e32 v122, v18, v130
	v_fmac_f32_e32 v123, v19, v131
	v_fmac_f32_e32 v124, v20, v132
	v_fmac_f32_e32 v125, v21, v133
	v_fmac_f32_e32 v126, v22, v134
	v_fmac_f32_e32 v127, v23, v135
	v_lshlrev_b32_e32 v128, 16, v52
; #define wt16(p, v) wt16b(WSB, (p), (v))
; __device__ __forceinline__ u32x4 pack8(const float (&f)[8]) { u32x4 v; v.x = cvt_pk_bf16(f[0], f[1]); v.y = cvt_pk_bf16(f[2], f[3]); v.z = cvt_pk_bf16(f[4], f[5]); v.w = cvt_pk_bf16(f[6], f[7]); return v; }
; __device__ __forceinline__ void conv_mixer_rows(CArgs a, int layer, int G) {
;     ...
;         for (int k = 0; k < 3; ++k) { float ch[8], cc[8]; unpack8(raw[2 * k], ch); unpack8(raw[2 * k + 1], cc);
; #pragma unroll
;             for (int e = 0; e < 8; ++e) accv[e] += w[k][e] * (cc[e] * ch[e]); }
;         float cbv[8]; unpack8(raw[6], cbv);
;         float ss = 0.f;
; #pragma unroll
;         for (int e = 0; e < 8; ++e) { accv[e] *= cbv[e]; ss += accv[e] * accv[e]; }
;         ss += __shfl_xor(ss, 1); ss += __shfl_xor(ss, 2); ss += __shfl_xor(ss, 4);
;         const float r = rsqrtf(ss * (1.f / 64.f) + EPS);
; #pragma unroll
;         for (int e = 0; e < 8; ++e) accv[e] *= r;
;         wt16(Y + (size_t)row * 2048 + 1536 + c0, pack8(accv));
;     };
;     for (int row = gw; row < T; row += 2 * NGW) {
;         const int row2 = row + NGW;
;         u32x4 ra[7], rb[7];
;         load(row, ra);
;         if (row2 < T) load(row2, rb);
;         finish(row, ra);
;         if (row2 < T) finish(row2, rb);
;     }
	v_and_b32_e32 v129, 0xffff0000, v52
	v_lshlrev_b32_e32 v130, 16, v53
	v_and_b32_e32 v131, 0xffff0000, v53
	v_lshlrev_b32_e32 v132, 16, v54
	v_and_b32_e32 v133, 0xffff0000, v54
	v_lshlrev_b32_e32 v134, 16, v55
	v_and_b32_e32 v135, 0xffff0000, v55
	v_lshlrev_b32_e32 v136, 16, v56
	v_and_b32_e32 v137, 0xffff0000, v56
	v_lshlrev_b32_e32 v138, 16, v57
	v_and_b32_e32 v139, 0xffff0000, v57
	v_lshlrev_b32_e32 v140, 16, v58
	v_and_b32_e32 v141, 0xffff0000, v58
	v_lshlrev_b32_e32 v142, 16, v59
	v_and_b32_e32 v143, 0xffff0000, v59
	v_mul_f32_e32 v128, v136, v128
	v_mul_f32_e32 v129, v137, v129
	v_mul_f32_e32 v130, v138, v130
	v_mul_f32_e32 v131, v139, v131
	v_mul_f32_e32 v132, v140, v132
	v_mul_f32_e32 v133, v141, v133
	v_mul_f32_e32 v134, v142, v134
	v_mul_f32_e32 v135, v143, v135
	v_fmac_f32_e32 v120, v24, v128
	v_fmac_f32_e32 v121, v25, v129
	v_fmac_f32_e32 v122, v26, v130
	v_fmac_f32_e32 v123, v27, v131
	v_fmac_f32_e32 v124, v28, v132
	v_fmac_f32_e32 v125, v29, v133
	v_fmac_f32_e32 v126, v30, v134
	v_fmac_f32_e32 v127, v31, v135
	v_lshlrev_b32_e32 v136, 16, v48
	v_and_b32_e32 v137, 0xffff0000, v48
	v_lshlrev_b32_e32 v138, 16, v49
	v_and_b32_e32 v139, 0xffff0000, v49
	v_lshlrev_b32_e32 v140, 16, v50
	v_and_b32_e32 v141, 0xffff0000, v50
	v_lshlrev_b32_e32 v142, 16, v51
	v_and_b32_e32 v143, 0xffff0000, v51
	v_mul_f32_e32 v120, v120, v136
	v_mul_f32_e32 v121, v121, v137
	v_mul_f32_e32 v122, v122, v138
	v_mul_f32_e32 v123, v123, v139
	v_mul_f32_e32 v124, v124, v140
	v_mul_f32_e32 v125, v125, v141
	v_mul_f32_e32 v126, v126, v142
	v_mul_f32_e32 v127, v127, v143
	v_mul_f32_e32 v144, v120, v120
	v_fmac_f32_e32 v144, v121, v121
	v_fmac_f32_e32 v144, v122, v122
	v_fmac_f32_e32 v144, v123, v123
	v_fmac_f32_e32 v144, v124, v124
	v_fmac_f32_e32 v144, v125, v125
	v_fmac_f32_e32 v144, v126, v126
	v_fmac_f32_e32 v144, v127, v127
	s_nop 1
	v_add_f32_dpp v144, v144, v144 quad_perm:[1,0,3,2] row_mask:0xf bank_mask:0xf
	s_nop 1
	v_add_f32_dpp v144, v144, v144 quad_perm:[2,3,0,1] row_mask:0xf bank_mask:0xf
	s_nop 1
	v_add_f32_dpp v144, v144, v144 row_half_mirror row_mask:0xf bank_mask:0xf
	v_fmamk_f32 v145, v144, 0x3c800000, v245
	v_rsq_f32_e32 v145, v145
	s_lshl_b32 s22, s10, 12
	s_add_u32 s22, s22, 0x10a00000
	v_mul_f32_e32 v120, v120, v145
	v_mul_f32_e32 v121, v121, v145
	v_mul_f32_e32 v122, v122, v145
	v_mul_f32_e32 v123, v123, v145
	v_mul_f32_e32 v124, v124, v145
	v_mul_f32_e32 v125, v125, v145
	v_mul_f32_e32 v126, v126, v145
	v_mul_f32_e32 v127, v127, v145
	v_cvt_pk_bf16_f32 v120, v120, v121
	v_cvt_pk_bf16_f32 v121, v122, v123
	v_cvt_pk_bf16_f32 v122, v124, v125
	v_cvt_pk_bf16_f32 v123, v126, v127
	buffer_store_dwordx4 v[120:123], v5, s[60:63], s22 offen sc1
	s_mul_i32 s17, s16, 3
	s_add_i32 s17, s10, s17
	s_cmp_lt_u32 s17, 0x4000
	s_cselect_b32 s17, s17, s10
	s_and_b32 s21, s17, 0x7ff
	s_mul_i32 s19, s17, 0x2400
	s_add_u32 s19, s19, 0x3a00000
	s_sub_u32 s18, s19, 0x2400
	s_add_u32 s20, s19, 0x2400
	s_cmp_eq_u32 s21, 0
	s_cselect_b32 s18, s19, s18
	s_cmpk_eq_u32 s21, 0x7ff
	s_cselect_b32 s20, s19, s20
	buffer_load_dwordx4 v[32:35], v2, s[60:63], s18 offen
	buffer_load_dwordx4 v[36:39], v3, s[60:63], s18 offen
	buffer_load_dwordx4 v[40:43], v2, s[60:63], s19 offen
	buffer_load_dwordx4 v[44:47], v3, s[60:63], s19 offen
	buffer_load_dwordx4 v[48:51], v4, s[60:63], s19 offen
	buffer_load_dwordx4 v[52:55], v2, s[60:63], s20 offen
	buffer_load_dwordx4 v[56:59], v3, s[60:63], s20 offen
	s_add_i32 s10, s10, s16
	s_cmp_lt_u32 s10, 0x4000
	s_cbranch_scc0 .Lcvm_done
	s_waitcnt vmcnt(15)
	s_and_b32 s21, s10, 0x7ff
	s_cmp_lg_u32 s21, 0
	s_cbranch_scc1 .Lcvm_nz0_2
	v_mov_b32_e32 v60, 0
	v_mov_b32_e32 v61, 0
	v_mov_b32_e32 v62, 0
	v_mov_b32_e32 v63, 0
.Lcvm_nz0_2:
	s_cmpk_lg_u32 s21, 0x7ff
	s_cbranch_scc1 .Lcvm_nz2_2
	v_mov_b32_e32 v80, 0
	v_mov_b32_e32 v81, 0
	v_mov_b32_e32 v82, 0
	v_mov_b32_e32 v83, 0
.Lcvm_nz2_2:
	v_lshlrev_b32_e32 v128, 16, v60
	v_and_b32_e32 v129, 0xffff0000, v60
	v_lshlrev_b32_e32 v130, 16, v61
	v_and_b32_e32 v131, 0xffff0000, v61
	v_lshlrev_b32_e32 v132, 16, v62
	v_and_b32_e32 v133, 0xffff0000, v62
	v_lshlrev_b32_e32 v134, 16, v63
	v_and_b32_e32 v135, 0xffff0000, v63
	v_lshlrev_b32_e32 v136, 16, v64
	v_and_b32_e32 v137, 0xffff0000, v64
	v_lshlrev_b32_e32 v138, 16, v65
	v_and_b32_e32 v139, 0xffff0000, v65
	v_lshlrev_b32_e32 v140, 16, v66
	v_and_b32_e32 v141, 0xffff0000, v66
	v_lshlrev_b32_e32 v142, 16, v67
	v_and_b32_e32 v143, 0xffff0000, v67
	v_mul_f32_e32 v128, v136, v128
	v_mul_f32_e32 v129, v137, v129
	v_mul_f32_e32 v130, v138, v130
	v_mul_f32_e32 v131, v139, v131
	v_mul_f32_e32 v132, v140, v132
	v_mul_f32_e32 v133, v141, v133
	v_mul_f32_e32 v134, v142, v134
	v_mul_f32_e32 v135, v143, v135
	v_mul_f32_e32 v120, v8, v128
	v_mul_f32_e32 v121, v9, v129
	v_mul_f32_e32 v122, v10, v130
	v_mul_f32_e32 v123, v11, v131
	v_mul_f32_e32 v124, v12, v132
	v_mul_f32_e32 v125, v13, v133
	v_mul_f32_e32 v126, v14, v134
	v_mul_f32_e32 v127, v15, v135
	v_lshlrev_b32_e32 v128, 16, v68
	v_and_b32_e32 v129, 0xffff0000, v68
	v_lshlrev_b32_e32 v130, 16, v69
	v_and_b32_e32 v131, 0xffff0000, v69
	v_lshlrev_b32_e32 v132, 16, v70
	v_and_b32_e32 v133, 0xffff0000, v70
	v_lshlrev_b32_e32 v134, 16, v71
	v_and_b32_e32 v135, 0xffff0000, v71
	v_lshlrev_b32_e32 v136, 16, v72
	v_and_b32_e32 v137, 0xffff0000, v72
	v_lshlrev_b32_e32 v138, 16, v73
	v_and_b32_e32 v139, 0xffff0000, v73
	v_lshlrev_b32_e32 v140, 16, v74
	v_and_b32_e32 v141, 0xffff0000, v74
	v_lshlrev_b32_e32 v142, 16, v75
	v_and_b32_e32 v143, 0xffff0000, v75
	v_mul_f32_e32 v128, v136, v128
	v_mul_f32_e32 v129, v137, v129
	v_mul_f32_e32 v130, v138, v130
	v_mul_f32_e32 v131, v139, v131
	v_mul_f32_e32 v132, v140, v132
; #define wt16(p, v) wt16b(WSB, (p), (v))
; __device__ __forceinline__ u32x4 pack8(const float (&f)[8]) { u32x4 v; v.x = cvt_pk_bf16(f[0], f[1]); v.y = cvt_pk_bf16(f[2], f[3]); v.z = cvt_pk_bf16(f[4], f[5]); v.w = cvt_pk_bf16(f[6], f[7]); return v; }
; __device__ __forceinline__ void conv_mixer_rows(CArgs a, int layer, int G) {
;     ...
;     auto finish = [&](int row, const u32x4 (&raw)[7]) {
;         float accv[8];
; #pragma unroll
;         for (int e = 0; e < 8; ++e) accv[e] = 0.f;
; #pragma unroll
;         for (int k = 0; k < 3; ++k) { float ch[8], cc[8]; unpack8(raw[2 * k], ch); unpack8(raw[2 * k + 1], cc);
; #pragma unroll
;             for (int e = 0; e < 8; ++e) accv[e] += w[k][e] * (cc[e] * ch[e]); }
;         float cbv[8]; unpack8(raw[6], cbv);
;         float ss = 0.f;
; #pragma unroll
;         for (int e = 0; e < 8; ++e) { accv[e] *= cbv[e]; ss += accv[e] * accv[e]; }
;         ss += __shfl_xor(ss, 1); ss += __shfl_xor(ss, 2); ss += __shfl_xor(ss, 4);
;         const float r = rsqrtf(ss * (1.f / 64.f) + EPS);
; #pragma unroll
;         for (int e = 0; e < 8; ++e) accv[e] *= r;
;         wt16(Y + (size_t)row * 2048 + 1536 + c0, pack8(accv));
;     };
;     for (int row = gw; row < T; row += 2 * NGW) {
;         const int row2 = row + NGW;
;         u32x4 ra[7], rb[7];
;         load(row, ra);
;         if (row2 < T) load(row2, rb);
;         finish(row, ra);
;         if (row2 < T) finish(row2, rb);
;     }
	v_mul_f32_e32 v133, v141, v133
	v_mul_f32_e32 v134, v142, v134
	v_mul_f32_e32 v135, v143, v135
	v_fmac_f32_e32 v120, v16, v128
	v_fmac_f32_e32 v121, v17, v129
	v_fmac_f32_e32 v122, v18, v130
	v_fmac_f32_e32 v123, v19, v131
	v_fmac_f32_e32 v124, v20, v132
	v_fmac_f32_e32 v125, v21, v133
	v_fmac_f32_e32 v126, v22, v134
	v_fmac_f32_e32 v127, v23, v135
	v_lshlrev_b32_e32 v128, 16, v80
	v_and_b32_e32 v129, 0xffff0000, v80
	v_lshlrev_b32_e32 v130, 16, v81
	v_and_b32_e32 v131, 0xffff0000, v81
	v_lshlrev_b32_e32 v132, 16, v82
	v_and_b32_e32 v133, 0xffff0000, v82
	v_lshlrev_b32_e32 v134, 16, v83
	v_and_b32_e32 v135, 0xffff0000, v83
	v_lshlrev_b32_e32 v136, 16, v84
	v_and_b32_e32 v137, 0xffff0000, v84
	v_lshlrev_b32_e32 v138, 16, v85
	v_and_b32_e32 v139, 0xffff0000, v85
	v_lshlrev_b32_e32 v140, 16, v86
	v_and_b32_e32 v141, 0xffff0000, v86
	v_lshlrev_b32_e32 v142, 16, v87
	v_and_b32_e32 v143, 0xffff0000, v87
	v_mul_f32_e32 v128, v136, v128
	v_mul_f32_e32 v129, v137, v129
	v_mul_f32_e32 v130, v138, v130
	v_mul_f32_e32 v131, v139, v131
	v_mul_f32_e32 v132, v140, v132
	v_mul_f32_e32 v133, v141, v133
	v_mul_f32_e32 v134, v142, v134
	v_mul_f32_e32 v135, v143, v135
	v_fmac_f32_e32 v120, v24, v128
	v_fmac_f32_e32 v121, v25, v129
	v_fmac_f32_e32 v122, v26, v130
	v_fmac_f32_e32 v123, v27, v131
	v_fmac_f32_e32 v124, v28, v132
	v_fmac_f32_e32 v125, v29, v133
	v_fmac_f32_e32 v126, v30, v134
	v_fmac_f32_e32 v127, v31, v135
	v_lshlrev_b32_e32 v136, 16, v76
	v_and_b32_e32 v137, 0xffff0000, v76
	v_lshlrev_b32_e32 v138, 16, v77
	v_and_b32_e32 v139, 0xffff0000, v77
	v_lshlrev_b32_e32 v140, 16, v78
	v_and_b32_e32 v141, 0xffff0000, v78
	v_lshlrev_b32_e32 v142, 16, v79
	v_and_b32_e32 v143, 0xffff0000, v79
	v_mul_f32_e32 v120, v120, v136
	v_mul_f32_e32 v121, v121, v137
	v_mul_f32_e32 v122, v122, v138
	v_mul_f32_e32 v123, v123, v139
	v_mul_f32_e32 v124, v124, v140
	v_mul_f32_e32 v125, v125, v141
	v_mul_f32_e32 v126, v126, v142
	v_mul_f32_e32 v127, v127, v143
	v_mul_f32_e32 v144, v120, v120
	v_fmac_f32_e32 v144, v121, v121
	v_fmac_f32_e32 v144, v122, v122
	v_fmac_f32_e32 v144, v123, v123
	v_fmac_f32_e32 v144, v124, v124
	v_fmac_f32_e32 v144, v125, v125
	v_fmac_f32_e32 v144, v126, v126
	v_fmac_f32_e32 v144, v127, v127
	s_nop 1
	v_add_f32_dpp v144, v144, v144 quad_perm:[1,0,3,2] row_mask:0xf bank_mask:0xf
	s_nop 1
	v_add_f32_dpp v144, v144, v144 quad_perm:[2,3,0,1] row_mask:0xf bank_mask:0xf
	s_nop 1
	v_add_f32_dpp v144, v144, v144 row_half_mirror row_mask:0xf bank_mask:0xf
	v_fmamk_f32 v145, v144, 0x3c800000, v245
	v_rsq_f32_e32 v145, v145
	s_lshl_b32 s22, s10, 12
	s_add_u32 s22, s22, 0x10a00000
	v_mul_f32_e32 v120, v120, v145
	v_mul_f32_e32 v121, v121, v145
	v_mul_f32_e32 v122, v122, v145
	v_mul_f32_e32 v123, v123, v145
	v_mul_f32_e32 v124, v124, v145
	v_mul_f32_e32 v125, v125, v145
	v_mul_f32_e32 v126, v126, v145
	v_mul_f32_e32 v127, v127, v145
	v_cvt_pk_bf16_f32 v120, v120, v121
	v_cvt_pk_bf16_f32 v121, v122, v123
	v_cvt_pk_bf16_f32 v122, v124, v125
	v_cvt_pk_bf16_f32 v123, v126, v127
	buffer_store_dwordx4 v[120:123], v5, s[60:63], s22 offen sc1
	s_mul_i32 s17, s16, 3
	s_add_i32 s17, s10, s17
	s_cmp_lt_u32 s17, 0x4000
	s_cselect_b32 s17, s17, s10
	s_and_b32 s21, s17, 0x7ff
	s_mul_i32 s19, s17, 0x2400
	s_add_u32 s19, s19, 0x3a00000
	s_sub_u32 s18, s19, 0x2400
	s_add_u32 s20, s19, 0x2400
	s_cmp_eq_u32 s21, 0
	s_cselect_b32 s18, s19, s18
	s_cmpk_eq_u32 s21, 0x7ff
	s_cselect_b32 s20, s19, s20
	buffer_load_dwordx4 v[60:63], v2, s[60:63], s18 offen
	buffer_load_dwordx4 v[64:67], v3, s[60:63], s18 offen
	buffer_load_dwordx4 v[68:71], v2, s[60:63], s19 offen
	buffer_load_dwordx4 v[72:75], v3, s[60:63], s19 offen
	buffer_load_dwordx4 v[76:79], v4, s[60:63], s19 offen
	buffer_load_dwordx4 v[80:83], v2, s[60:63], s20 offen
	buffer_load_dwordx4 v[84:87], v3, s[60:63], s20 offen
	s_add_i32 s10, s10, s16
	s_cmp_lt_u32 s10, 0x4000
	s_cbranch_scc0 .Lcvm_done
	s_waitcnt vmcnt(16)
	s_and_b32 s21, s10, 0x7ff
	s_cmp_lg_u32 s21, 0
	s_cbranch_scc1 .Lcvm_nz0_3
	v_mov_b32_e32 v88, 0
	v_mov_b32_e32 v89, 0
	v_mov_b32_e32 v90, 0
	v_mov_b32_e32 v91, 0
.Lcvm_nz0_3:
	s_cmpk_lg_u32 s21, 0x7ff
	s_cbranch_scc1 .Lcvm_nz2_3
	v_mov_b32_e32 v108, 0
	v_mov_b32_e32 v109, 0
	v_mov_b32_e32 v110, 0
	v_mov_b32_e32 v111, 0
; #define wt16(p, v) wt16b(WSB, (p), (v))
; __device__ __forceinline__ u32x4 pack8(const float (&f)[8]) { u32x4 v; v.x = cvt_pk_bf16(f[0], f[1]); v.y = cvt_pk_bf16(f[2], f[3]); v.z = cvt_pk_bf16(f[4], f[5]); v.w = cvt_pk_bf16(f[6], f[7]); return v; }
; __device__ __forceinline__ void conv_mixer_rows(CArgs a, int layer, int G) {
;     ...
;     auto finish = [&](int row, const u32x4 (&raw)[7]) {
;         float accv[8];
; #pragma unroll
;         for (int e = 0; e < 8; ++e) accv[e] = 0.f;
; #pragma unroll
;         for (int k = 0; k < 3; ++k) { float ch[8], cc[8]; unpack8(raw[2 * k], ch); unpack8(raw[2 * k + 1], cc);
; #pragma unroll
;             for (int e = 0; e < 8; ++e) accv[e] += w[k][e] * (cc[e] * ch[e]); }
;         float cbv[8]; unpack8(raw[6], cbv);
;         float ss = 0.f;
; #pragma unroll
;         for (int e = 0; e < 8; ++e) { accv[e] *= cbv[e]; ss += accv[e] * accv[e]; }
;         ss += __shfl_xor(ss, 1); ss += __shfl_xor(ss, 2); ss += __shfl_xor(ss, 4);
;         const float r = rsqrtf(ss * (1.f / 64.f) + EPS);
; #pragma unroll
;         for (int e = 0; e < 8; ++e) accv[e] *= r;
;         wt16(Y + (size_t)row * 2048 + 1536 + c0, pack8(accv));
;     };
;     for (int row = gw; row < T; row += 2 * NGW) {
;         const int row2 = row + NGW;
;         u32x4 ra[7], rb[7];
;         load(row, ra);
;         if (row2 < T) load(row2, rb);
;         finish(row, ra);
;         if (row2 < T) finish(row2, rb);
;     }
.Lcvm_nz2_3:
	v_lshlrev_b32_e32 v128, 16, v88
	v_and_b32_e32 v129, 0xffff0000, v88
	v_lshlrev_b32_e32 v130, 16, v89
	v_and_b32_e32 v131, 0xffff0000, v89
	v_lshlrev_b32_e32 v132, 16, v90
	v_and_b32_e32 v133, 0xffff0000, v90
	v_lshlrev_b32_e32 v134, 16, v91
	v_and_b32_e32 v135, 0xffff0000, v91
	v_lshlrev_b32_e32 v136, 16, v92
	v_and_b32_e32 v137, 0xffff0000, v92
	v_lshlrev_b32_e32 v138, 16, v93
	v_and_b32_e32 v139, 0xffff0000, v93
	v_lshlrev_b32_e32 v140, 16, v94
	v_and_b32_e32 v141, 0xffff0000, v94
	v_lshlrev_b32_e32 v142, 16, v95
	v_and_b32_e32 v143, 0xffff0000, v95
	v_mul_f32_e32 v128, v136, v128
	v_mul_f32_e32 v129, v137, v129
	v_mul_f32_e32 v130, v138, v130
	v_mul_f32_e32 v131, v139, v131
	v_mul_f32_e32 v132, v140, v132
	v_mul_f32_e32 v133, v141, v133
	v_mul_f32_e32 v134, v142, v134
	v_mul_f32_e32 v135, v143, v135
	v_mul_f32_e32 v120, v8, v128
	v_mul_f32_e32 v121, v9, v129
	v_mul_f32_e32 v122, v10, v130
	v_mul_f32_e32 v123, v11, v131
	v_mul_f32_e32 v124, v12, v132
	v_mul_f32_e32 v125, v13, v133
	v_mul_f32_e32 v126, v14, v134
	v_mul_f32_e32 v127, v15, v135
	v_lshlrev_b32_e32 v128, 16, v96
	v_and_b32_e32 v129, 0xffff0000, v96
	v_lshlrev_b32_e32 v130, 16, v97
	v_and_b32_e32 v131, 0xffff0000, v97
	v_lshlrev_b32_e32 v132, 16, v98
	v_and_b32_e32 v133, 0xffff0000, v98
	v_lshlrev_b32_e32 v134, 16, v99
	v_and_b32_e32 v135, 0xffff0000, v99
	v_lshlrev_b32_e32 v136, 16, v100
	v_and_b32_e32 v137, 0xffff0000, v100
	v_lshlrev_b32_e32 v138, 16, v101
	v_and_b32_e32 v139, 0xffff0000, v101
	v_lshlrev_b32_e32 v140, 16, v102
	v_and_b32_e32 v141, 0xffff0000, v102
	v_lshlrev_b32_e32 v142, 16, v103
	v_and_b32_e32 v143, 0xffff0000, v103
	v_mul_f32_e32 v128, v136, v128
	v_mul_f32_e32 v129, v137, v129
	v_mul_f32_e32 v130, v138, v130
	v_mul_f32_e32 v131, v139, v131
	v_mul_f32_e32 v132, v140, v132
	v_mul_f32_e32 v133, v141, v133
	v_mul_f32_e32 v134, v142, v134
	v_mul_f32_e32 v135, v143, v135
	v_fmac_f32_e32 v120, v16, v128
	v_fmac_f32_e32 v121, v17, v129
	v_fmac_f32_e32 v122, v18, v130
	v_fmac_f32_e32 v123, v19, v131
	v_fmac_f32_e32 v124, v20, v132
	v_fmac_f32_e32 v125, v21, v133
	v_fmac_f32_e32 v126, v22, v134
	v_fmac_f32_e32 v127, v23, v135
	v_lshlrev_b32_e32 v128, 16, v108
	v_and_b32_e32 v129, 0xffff0000, v108
	v_lshlrev_b32_e32 v130, 16, v109
	v_and_b32_e32 v131, 0xffff0000, v109
	v_lshlrev_b32_e32 v132, 16, v110
	v_and_b32_e32 v133, 0xffff0000, v110
	v_lshlrev_b32_e32 v134, 16, v111
	v_and_b32_e32 v135, 0xffff0000, v111
	v_lshlrev_b32_e32 v136, 16, v112
	v_and_b32_e32 v137, 0xffff0000, v112
	v_lshlrev_b32_e32 v138, 16, v113
	v_and_b32_e32 v139, 0xffff0000, v113
	v_lshlrev_b32_e32 v140, 16, v114
	v_and_b32_e32 v141, 0xffff0000, v114
	v_lshlrev_b32_e32 v142, 16, v115
	v_and_b32_e32 v143, 0xffff0000, v115
	v_mul_f32_e32 v128, v136, v128
	v_mul_f32_e32 v129, v137, v129
	v_mul_f32_e32 v130, v138, v130
	v_mul_f32_e32 v131, v139, v131
	v_mul_f32_e32 v132, v140, v132
	v_mul_f32_e32 v133, v141, v133
	v_mul_f32_e32 v134, v142, v134
	v_mul_f32_e32 v135, v143, v135
	v_fmac_f32_e32 v120, v24, v128
	v_fmac_f32_e32 v121, v25, v129
	v_fmac_f32_e32 v122, v26, v130
	v_fmac_f32_e32 v123, v27, v131
	v_fmac_f32_e32 v124, v28, v132
	v_fmac_f32_e32 v125, v29, v133
	v_fmac_f32_e32 v126, v30, v134
	v_fmac_f32_e32 v127, v31, v135
	v_lshlrev_b32_e32 v136, 16, v104
	v_and_b32_e32 v137, 0xffff0000, v104
	v_lshlrev_b32_e32 v138, 16, v105
	v_and_b32_e32 v139, 0xffff0000, v105
	v_lshlrev_b32_e32 v140, 16, v106
	v_and_b32_e32 v141, 0xffff0000, v106
	v_lshlrev_b32_e32 v142, 16, v107
	v_and_b32_e32 v143, 0xffff0000, v107
	v_mul_f32_e32 v120, v120, v136
	v_mul_f32_e32 v121, v121, v137
	v_mul_f32_e32 v122, v122, v138
	v_mul_f32_e32 v123, v123, v139
	v_mul_f32_e32 v124, v124, v140
	v_mul_f32_e32 v125, v125, v141
	v_mul_f32_e32 v126, v126, v142
	v_mul_f32_e32 v127, v127, v143
	v_mul_f32_e32 v144, v120, v120
	v_fmac_f32_e32 v144, v121, v121
	v_fmac_f32_e32 v144, v122, v122
	v_fmac_f32_e32 v144, v123, v123
	v_fmac_f32_e32 v144, v124, v124
	v_fmac_f32_e32 v144, v125, v125
	v_fmac_f32_e32 v144, v126, v126
	v_fmac_f32_e32 v144, v127, v127
	s_nop 1
	v_add_f32_dpp v144, v144, v144 quad_perm:[1,0,3,2] row_mask:0xf bank_mask:0xf
	s_nop 1
	v_add_f32_dpp v144, v144, v144 quad_perm:[2,3,0,1] row_mask:0xf bank_mask:0xf
	s_nop 1
	v_add_f32_dpp v144, v144, v144 row_half_mirror row_mask:0xf bank_mask:0xf
	v_fmamk_f32 v145, v144, 0x3c800000, v245
	v_rsq_f32_e32 v145, v145
	s_lshl_b32 s22, s10, 12
	s_add_u32 s22, s22, 0x10a00000
	v_mul_f32_e32 v120, v120, v145
	v_mul_f32_e32 v121, v121, v145
	v_mul_f32_e32 v122, v122, v145
	v_mul_f32_e32 v123, v123, v145
	v_mul_f32_e32 v124, v124, v145
	v_mul_f32_e32 v125, v125, v145
	v_mul_f32_e32 v126, v126, v145
	v_mul_f32_e32 v127, v127, v145
	v_cvt_pk_bf16_f32 v120, v120, v121
	v_cvt_pk_bf16_f32 v121, v122, v123
	v_cvt_pk_bf16_f32 v122, v124, v125
	v_cvt_pk_bf16_f32 v123, v126, v127
	buffer_store_dwordx4 v[120:123], v5, s[60:63], s22 offen sc1
	s_mul_i32 s17, s16, 3
	s_add_i32 s17, s10, s17
	s_cmp_lt_u32 s17, 0x4000
	s_cselect_b32 s17, s17, s10
	s_and_b32 s21, s17, 0x7ff
	s_mul_i32 s19, s17, 0x2400
	s_add_u32 s19, s19, 0x3a00000
	s_sub_u32 s18, s19, 0x2400
	s_add_u32 s20, s19, 0x2400
	s_cmp_eq_u32 s21, 0
	s_cselect_b32 s18, s19, s18
	s_cmpk_eq_u32 s21, 0x7ff
	s_cselect_b32 s20, s19, s20
	buffer_load_dwordx4 v[88:91], v2, s[60:63], s18 offen
	buffer_load_dwordx4 v[92:95], v3, s[60:63], s18 offen
	buffer_load_dwordx4 v[96:99], v2, s[60:63], s19 offen
	buffer_load_dwordx4 v[100:103], v3, s[60:63], s19 offen
	buffer_load_dwordx4 v[104:107], v4, s[60:63], s19 offen
	buffer_load_dwordx4 v[108:111], v2, s[60:63], s20 offen
	buffer_load_dwordx4 v[112:115], v3, s[60:63], s20 offen
	s_add_i32 s10, s10, s16
	s_cmp_lt_u32 s10, 0x4000
	s_cbranch_scc0 .Lcvm_done
.Lcvm_loop:
	s_waitcnt vmcnt(16)
	s_and_b32 s21, s10, 0x7ff
	s_cmp_lg_u32 s21, 0
	s_cbranch_scc1 .Lcvm_nz0_4
	v_mov_b32_e32 v32, 0
	v_mov_b32_e32 v33, 0
	v_mov_b32_e32 v34, 0
	v_mov_b32_e32 v35, 0

; #define wt16(p, v) wt16b(WSB, (p), (v))
; __device__ __forceinline__ u32x4 pack8(const float (&f)[8]) { u32x4 v; v.x = cvt_pk_bf16(f[0], f[1]); v.y = cvt_pk_bf16(f[2], f[3]); v.z = cvt_pk_bf16(f[4], f[5]); v.w = cvt_pk_bf16(f[6], f[7]); return v; }
; __device__ __forceinline__ void conv_mixer_rows(CArgs a, int layer, int G) {
;     ...
;     auto finish = [&](int row, const u32x4 (&raw)[7]) {
;         float accv[8];
; #pragma unroll
;         for (int e = 0; e < 8; ++e) accv[e] = 0.f;
; #pragma unroll
;         for (int k = 0; k < 3; ++k) { float ch[8], cc[8]; unpack8(raw[2 * k], ch); unpack8(raw[2 * k + 1], cc);
; #pragma unroll
;             for (int e = 0; e < 8; ++e) accv[e] += w[k][e] * (cc[e] * ch[e]); }
;         float cbv[8]; unpack8(raw[6], cbv);
;         float ss = 0.f;
; #pragma unroll
;         for (int e = 0; e < 8; ++e) { accv[e] *= cbv[e]; ss += accv[e] * accv[e]; }
;         ss += __shfl_xor(ss, 1); ss += __shfl_xor(ss, 2); ss += __shfl_xor(ss, 4);
;         const float r = rsqrtf(ss * (1.f / 64.f) + EPS);
; #pragma unroll
;         for (int e = 0; e < 8; ++e) accv[e] *= r;
;         wt16(Y + (size_t)row * 2048 + 1536 + c0, pack8(accv));
;     };
;     for (int row = gw; row < T; row += 2 * NGW) {
;         const int row2 = row + NGW;
;         u32x4 ra[7], rb[7];
;         load(row, ra);
;         if (row2 < T) load(row2, rb);
;         finish(row, ra);
;         if (row2 < T) finish(row2, rb);
;     }
.Lcvm_nz2_4:
	v_lshlrev_b32_e32 v128, 16, v32
	v_and_b32_e32 v129, 0xffff0000, v32
	v_lshlrev_b32_e32 v130, 16, v33
	v_and_b32_e32 v131, 0xffff0000, v33
	v_lshlrev_b32_e32 v132, 16, v34
	v_and_b32_e32 v133, 0xffff0000, v34
	v_lshlrev_b32_e32 v134, 16, v35
	v_and_b32_e32 v135, 0xffff0000, v35
	v_lshlrev_b32_e32 v136, 16, v36
	v_and_b32_e32 v137, 0xffff0000, v36
	v_lshlrev_b32_e32 v138, 16, v37
	v_and_b32_e32 v139, 0xffff0000, v37
	v_lshlrev_b32_e32 v140, 16, v38
	v_and_b32_e32 v141, 0xffff0000, v38
	v_lshlrev_b32_e32 v142, 16, v39
	v_and_b32_e32 v143, 0xffff0000, v39
	v_mul_f32_e32 v128, v136, v128
	v_mul_f32_e32 v129, v137, v129
	v_mul_f32_e32 v130, v138, v130
	v_mul_f32_e32 v131, v139, v131
	v_mul_f32_e32 v132, v140, v132
	v_mul_f32_e32 v133, v141, v133
	v_mul_f32_e32 v134, v142, v134
	v_mul_f32_e32 v135, v143, v135
	v_mul_f32_e32 v120, v8, v128
	v_mul_f32_e32 v121, v9, v129
	v_mul_f32_e32 v122, v10, v130
	v_mul_f32_e32 v123, v11, v131
	v_mul_f32_e32 v124, v12, v132
	v_mul_f32_e32 v125, v13, v133
	v_mul_f32_e32 v126, v14, v134
	v_mul_f32_e32 v127, v15, v135
	v_lshlrev_b32_e32 v128, 16, v40
	v_and_b32_e32 v129, 0xffff0000, v40
	v_lshlrev_b32_e32 v130, 16, v41
	v_and_b32_e32 v131, 0xffff0000, v41
	v_lshlrev_b32_e32 v132, 16, v42
	v_and_b32_e32 v133, 0xffff0000, v42
	v_lshlrev_b32_e32 v134, 16, v43
	v_and_b32_e32 v135, 0xffff0000, v43
	v_lshlrev_b32_e32 v136, 16, v44
	v_and_b32_e32 v137, 0xffff0000, v44
	v_lshlrev_b32_e32 v138, 16, v45
	v_and_b32_e32 v139, 0xffff0000, v45
	v_lshlrev_b32_e32 v140, 16, v46
	v_and_b32_e32 v141, 0xffff0000, v46
	v_lshlrev_b32_e32 v142, 16, v47
	v_and_b32_e32 v143, 0xffff0000, v47
	v_mul_f32_e32 v128, v136, v128
	v_mul_f32_e32 v129, v137, v129
	v_mul_f32_e32 v130, v138, v130
	v_mul_f32_e32 v131, v139, v131
	v_mul_f32_e32 v132, v140, v132
	v_mul_f32_e32 v133, v141, v133
	v_mul_f32_e32 v134, v142, v134
	v_mul_f32_e32 v135, v143, v135
	v_fmac_f32_e32 v120, v16, v128
	v_fmac_f32_e32 v121, v17, v129
	v_fmac_f32_e32 v122, v18, v130
	v_fmac_f32_e32 v123, v19, v131
	v_fmac_f32_e32 v124, v20, v132
	v_fmac_f32_e32 v125, v21, v133
	v_fmac_f32_e32 v126, v22, v134
	v_fmac_f32_e32 v127, v23, v135
	v_lshlrev_b32_e32 v128, 16, v52
	v_and_b32_e32 v129, 0xffff0000, v52
	v_lshlrev_b32_e32 v130, 16, v53
	v_and_b32_e32 v131, 0xffff0000, v53
	v_lshlrev_b32_e32 v132, 16, v54
	v_and_b32_e32 v133, 0xffff0000, v54
	v_lshlrev_b32_e32 v134, 16, v55
	v_and_b32_e32 v135, 0xffff0000, v55
	v_lshlrev_b32_e32 v136, 16, v56
	v_and_b32_e32 v137, 0xffff0000, v56
	v_lshlrev_b32_e32 v138, 16, v57
	v_and_b32_e32 v139, 0xffff0000, v57
	v_lshlrev_b32_e32 v140, 16, v58
	v_and_b32_e32 v141, 0xffff0000, v58
	v_lshlrev_b32_e32 v142, 16, v59
	v_and_b32_e32 v143, 0xffff0000, v59
	v_mul_f32_e32 v128, v136, v128
	v_mul_f32_e32 v129, v137, v129
	v_mul_f32_e32 v130, v138, v130
	v_mul_f32_e32 v131, v139, v131
	v_mul_f32_e32 v132, v140, v132
	v_mul_f32_e32 v133, v141, v133
	v_mul_f32_e32 v134, v142, v134
	v_mul_f32_e32 v135, v143, v135
	v_fmac_f32_e32 v120, v24, v128
	v_fmac_f32_e32 v121, v25, v129
	v_fmac_f32_e32 v122, v26, v130
	v_fmac_f32_e32 v123, v27, v131
	v_fmac_f32_e32 v124, v28, v132
	v_fmac_f32_e32 v125, v29, v133
	v_fmac_f32_e32 v126, v30, v134
	v_fmac_f32_e32 v127, v31, v135
	v_lshlrev_b32_e32 v136, 16, v48
	v_and_b32_e32 v137, 0xffff0000, v48
	v_lshlrev_b32_e32 v138, 16, v49
	v_and_b32_e32 v139, 0xffff0000, v49
	v_lshlrev_b32_e32 v140, 16, v50
	v_and_b32_e32 v141, 0xffff0000, v50
	v_lshlrev_b32_e32 v142, 16, v51
	v_and_b32_e32 v143, 0xffff0000, v51
	v_mul_f32_e32 v120, v120, v136
	v_mul_f32_e32 v121, v121, v137
	v_mul_f32_e32 v122, v122, v138
	v_mul_f32_e32 v123, v123, v139
	v_mul_f32_e32 v124, v124, v140
	v_mul_f32_e32 v125, v125, v141
	v_mul_f32_e32 v126, v126, v142
	v_mul_f32_e32 v127, v127, v143
	v_mul_f32_e32 v144, v120, v120
	v_fmac_f32_e32 v144, v121, v121
	v_fmac_f32_e32 v144, v122, v122
	v_fmac_f32_e32 v144, v123, v123
	v_fmac_f32_e32 v144, v124, v124
	v_fmac_f32_e32 v144, v125, v125
	v_fmac_f32_e32 v144, v126, v126
	v_fmac_f32_e32 v144, v127, v127
	s_nop 1
	v_add_f32_dpp v144, v144, v144 quad_perm:[1,0,3,2] row_mask:0xf bank_mask:0xf
	s_nop 1
	v_add_f32_dpp v144, v144, v144 quad_perm:[2,3,0,1] row_mask:0xf bank_mask:0xf
	s_nop 1
	v_add_f32_dpp v144, v144, v144 row_half_mirror row_mask:0xf bank_mask:0xf
	v_fmamk_f32 v145, v144, 0x3c800000, v245
	v_rsq_f32_e32 v145, v145
	s_lshl_b32 s22, s10, 12
	s_add_u32 s22, s22, 0x10a00000
	v_mul_f32_e32 v120, v120, v145
	v_mul_f32_e32 v121, v121, v145
	v_mul_f32_e32 v122, v122, v145
	v_mul_f32_e32 v123, v123, v145
	v_mul_f32_e32 v124, v124, v145
	v_mul_f32_e32 v125, v125, v145
	v_mul_f32_e32 v126, v126, v145
	v_mul_f32_e32 v127, v127, v145
	v_cvt_pk_bf16_f32 v120, v120, v121
	v_cvt_pk_bf16_f32 v121, v122, v123
	v_cvt_pk_bf16_f32 v122, v124, v125
	v_cvt_pk_bf16_f32 v123, v126, v127
	buffer_store_dwordx4 v[120:123], v5, s[60:63], s22 offen sc1
	s_mul_i32 s17, s16, 3
	s_add_i32 s17, s10, s17
	s_cmp_lt_u32 s17, 0x4000
	s_cselect_b32 s17, s17, s10
	s_and_b32 s21, s17, 0x7ff
	s_mul_i32 s19, s17, 0x2400
	s_add_u32 s19, s19, 0x3a00000
	s_sub_u32 s18, s19, 0x2400
	s_add_u32 s20, s19, 0x2400
	s_cmp_eq_u32 s21, 0
	s_cselect_b32 s18, s19, s18
	s_cmpk_eq_u32 s21, 0x7ff
	s_cselect_b32 s20, s19, s20
	buffer_load_dwordx4 v[32:35], v2, s[60:63], s18 offen
	buffer_load_dwordx4 v[36:39], v3, s[60:63], s18 offen
	buffer_load_dwordx4 v[40:43], v2, s[60:63], s19 offen
	buffer_load_dwordx4 v[44:47], v3, s[60:63], s19 offen
	buffer_load_dwordx4 v[48:51], v4, s[60:63], s19 offen
	buffer_load_dwordx4 v[52:55], v2, s[60:63], s20 offen
	buffer_load_dwordx4 v[56:59], v3, s[60:63], s20 offen
	s_add_i32 s10, s10, s16
	s_cmp_lt_u32 s10, 0x4000
	s_cbranch_scc0 .Lcvm_done
	s_waitcnt vmcnt(16)
	s_and_b32 s21, s10, 0x7ff
	s_cmp_lg_u32 s21, 0
	s_cbranch_scc1 .Lcvm_nz0_5
	v_mov_b32_e32 v60, 0
	v_mov_b32_e32 v61, 0
	v_mov_b32_e32 v62, 0
	v_mov_b32_e32 v63, 0

; #define wt16(p, v) wt16b(WSB, (p), (v))
; __device__ __forceinline__ u32x4 pack8(const float (&f)[8]) { u32x4 v; v.x = cvt_pk_bf16(f[0], f[1]); v.y = cvt_pk_bf16(f[2], f[3]); v.z = cvt_pk_bf16(f[4], f[5]); v.w = cvt_pk_bf16(f[6], f[7]); return v; }
; __device__ __forceinline__ void conv_mixer_rows(CArgs a, int layer, int G) {
;     ...
;     auto finish = [&](int row, const u32x4 (&raw)[7]) {
;         float accv[8];
; #pragma unroll
;         for (int e = 0; e < 8; ++e) accv[e] = 0.f;
; #pragma unroll
;         for (int k = 0; k < 3; ++k) { float ch[8], cc[8]; unpack8(raw[2 * k], ch); unpack8(raw[2 * k + 1], cc);
; #pragma unroll
;             for (int e = 0; e < 8; ++e) accv[e] += w[k][e] * (cc[e] * ch[e]); }
;         float cbv[8]; unpack8(raw[6], cbv);
;         float ss = 0.f;
; #pragma unroll
;         for (int e = 0; e < 8; ++e) { accv[e] *= cbv[e]; ss += accv[e] * accv[e]; }
;         ss += __shfl_xor(ss, 1); ss += __shfl_xor(ss, 2); ss += __shfl_xor(ss, 4);
;         const float r = rsqrtf(ss * (1.f / 64.f) + EPS);
; #pragma unroll
;         for (int e = 0; e < 8; ++e) accv[e] *= r;
;         wt16(Y + (size_t)row * 2048 + 1536 + c0, pack8(accv));
;     };
;     for (int row = gw; row < T; row += 2 * NGW) {
;         const int row2 = row + NGW;
;         u32x4 ra[7], rb[7];
;         load(row, ra);
;         if (row2 < T) load(row2, rb);
;         finish(row, ra);
;         if (row2 < T) finish(row2, rb);
;     }
; }
.Lcvm_nz2_6:
	v_lshlrev_b32_e32 v128, 16, v88
	v_and_b32_e32 v129, 0xffff0000, v88
	v_lshlrev_b32_e32 v130, 16, v89
	v_and_b32_e32 v131, 0xffff0000, v89
	v_lshlrev_b32_e32 v132, 16, v90
	v_and_b32_e32 v133, 0xffff0000, v90
	v_lshlrev_b32_e32 v134, 16, v91
	v_and_b32_e32 v135, 0xffff0000, v91
	v_lshlrev_b32_e32 v136, 16, v92
	v_and_b32_e32 v137, 0xffff0000, v92
	v_lshlrev_b32_e32 v138, 16, v93
	v_and_b32_e32 v139, 0xffff0000, v93
	v_lshlrev_b32_e32 v140, 16, v94
	v_and_b32_e32 v141, 0xffff0000, v94
	v_lshlrev_b32_e32 v142, 16, v95
	v_and_b32_e32 v143, 0xffff0000, v95
	v_mul_f32_e32 v128, v136, v128
	v_mul_f32_e32 v129, v137, v129
	v_mul_f32_e32 v130, v138, v130
	v_mul_f32_e32 v131, v139, v131
	v_mul_f32_e32 v132, v140, v132
	v_mul_f32_e32 v133, v141, v133
	v_mul_f32_e32 v134, v142, v134
	v_mul_f32_e32 v135, v143, v135
	v_mul_f32_e32 v120, v8, v128
	v_mul_f32_e32 v121, v9, v129
	v_mul_f32_e32 v122, v10, v130
	v_mul_f32_e32 v123, v11, v131
	v_mul_f32_e32 v124, v12, v132
	v_mul_f32_e32 v125, v13, v133
	v_mul_f32_e32 v126, v14, v134
	v_mul_f32_e32 v127, v15, v135
	v_lshlrev_b32_e32 v128, 16, v96
	v_and_b32_e32 v129, 0xffff0000, v96
	v_lshlrev_b32_e32 v130, 16, v97
	v_and_b32_e32 v131, 0xffff0000, v97
	v_lshlrev_b32_e32 v132, 16, v98
	v_and_b32_e32 v133, 0xffff0000, v98
	v_lshlrev_b32_e32 v134, 16, v99
	v_and_b32_e32 v135, 0xffff0000, v99
	v_lshlrev_b32_e32 v136, 16, v100
	v_and_b32_e32 v137, 0xffff0000, v100
	v_lshlrev_b32_e32 v138, 16, v101
	v_and_b32_e32 v139, 0xffff0000, v101
	v_lshlrev_b32_e32 v140, 16, v102
	v_and_b32_e32 v141, 0xffff0000, v102
	v_lshlrev_b32_e32 v142, 16, v103
	v_and_b32_e32 v143, 0xffff0000, v103
	v_mul_f32_e32 v128, v136, v128
	v_mul_f32_e32 v129, v137, v129
	v_mul_f32_e32 v130, v138, v130
	v_mul_f32_e32 v131, v139, v131
	v_mul_f32_e32 v132, v140, v132
	v_mul_f32_e32 v133, v141, v133
	v_mul_f32_e32 v134, v142, v134
	v_mul_f32_e32 v135, v143, v135
	v_fmac_f32_e32 v120, v16, v128
	v_fmac_f32_e32 v121, v17, v129
	v_fmac_f32_e32 v122, v18, v130
	v_fmac_f32_e32 v123, v19, v131
	v_fmac_f32_e32 v124, v20, v132
	v_fmac_f32_e32 v125, v21, v133
	v_fmac_f32_e32 v126, v22, v134
	v_fmac_f32_e32 v127, v23, v135
	v_lshlrev_b32_e32 v128, 16, v108
	v_and_b32_e32 v129, 0xffff0000, v108
	v_lshlrev_b32_e32 v130, 16, v109
	v_and_b32_e32 v131, 0xffff0000, v109
	v_lshlrev_b32_e32 v132, 16, v110
	v_and_b32_e32 v133, 0xffff0000, v110
	v_lshlrev_b32_e32 v134, 16, v111
	v_and_b32_e32 v135, 0xffff0000, v111
	v_lshlrev_b32_e32 v136, 16, v112
	v_and_b32_e32 v137, 0xffff0000, v112
	v_lshlrev_b32_e32 v138, 16, v113
	v_and_b32_e32 v139, 0xffff0000, v113
	v_lshlrev_b32_e32 v140, 16, v114
	v_and_b32_e32 v141, 0xffff0000, v114
	v_lshlrev_b32_e32 v142, 16, v115
	v_and_b32_e32 v143, 0xffff0000, v115
	v_mul_f32_e32 v128, v136, v128
	v_mul_f32_e32 v129, v137, v129
	v_mul_f32_e32 v130, v138, v130
	v_mul_f32_e32 v131, v139, v131
	v_mul_f32_e32 v132, v140, v132
	v_mul_f32_e32 v133, v141, v133
	v_mul_f32_e32 v134, v142, v134
	v_mul_f32_e32 v135, v143, v135
	v_fmac_f32_e32 v120, v24, v128
	v_fmac_f32_e32 v121, v25, v129
	v_fmac_f32_e32 v122, v26, v130
	v_fmac_f32_e32 v123, v27, v131
	v_fmac_f32_e32 v124, v28, v132
	v_fmac_f32_e32 v125, v29, v133
	v_fmac_f32_e32 v126, v30, v134
	v_fmac_f32_e32 v127, v31, v135
	v_lshlrev_b32_e32 v136, 16, v104
	v_and_b32_e32 v137, 0xffff0000, v104
	v_lshlrev_b32_e32 v138, 16, v105
	v_and_b32_e32 v139, 0xffff0000, v105
	v_lshlrev_b32_e32 v140, 16, v106
	v_and_b32_e32 v141, 0xffff0000, v106
	v_lshlrev_b32_e32 v142, 16, v107
	v_and_b32_e32 v143, 0xffff0000, v107
	v_mul_f32_e32 v120, v120, v136
	v_mul_f32_e32 v121, v121, v137
	v_mul_f32_e32 v122, v122, v138
	v_mul_f32_e32 v123, v123, v139
	v_mul_f32_e32 v124, v124, v140
	v_mul_f32_e32 v125, v125, v141
	v_mul_f32_e32 v126, v126, v142
	v_mul_f32_e32 v127, v127, v143
	v_mul_f32_e32 v144, v120, v120
	v_fmac_f32_e32 v144, v121, v121
	v_fmac_f32_e32 v144, v122, v122
	v_fmac_f32_e32 v144, v123, v123
	v_fmac_f32_e32 v144, v124, v124
	v_fmac_f32_e32 v144, v125, v125
	v_fmac_f32_e32 v144, v126, v126
	v_fmac_f32_e32 v144, v127, v127
	s_nop 1
	v_add_f32_dpp v144, v144, v144 quad_perm:[1,0,3,2] row_mask:0xf bank_mask:0xf
	s_nop 1
	v_add_f32_dpp v144, v144, v144 quad_perm:[2,3,0,1] row_mask:0xf bank_mask:0xf
	s_nop 1
	v_add_f32_dpp v144, v144, v144 row_half_mirror row_mask:0xf bank_mask:0xf
	v_fmamk_f32 v145, v144, 0x3c800000, v245
	v_rsq_f32_e32 v145, v145
	s_lshl_b32 s22, s10, 12
	s_add_u32 s22, s22, 0x10a00000
	v_mul_f32_e32 v120, v120, v145
	v_mul_f32_e32 v121, v121, v145
	v_mul_f32_e32 v122, v122, v145
	v_mul_f32_e32 v123, v123, v145
	v_mul_f32_e32 v124, v124, v145
	v_mul_f32_e32 v125, v125, v145
	v_mul_f32_e32 v126, v126, v145
	v_mul_f32_e32 v127, v127, v145
	v_cvt_pk_bf16_f32 v120, v120, v121
	v_cvt_pk_bf16_f32 v121, v122, v123
	v_cvt_pk_bf16_f32 v122, v124, v125
	v_cvt_pk_bf16_f32 v123, v126, v127
	buffer_store_dwordx4 v[120:123], v5, s[60:63], s22 offen sc1
	s_mul_i32 s17, s16, 3
	s_add_i32 s17, s10, s17
	s_cmp_lt_u32 s17, 0x4000
	s_cselect_b32 s17, s17, s10
	s_and_b32 s21, s17, 0x7ff
	s_mul_i32 s19, s17, 0x2400
	s_add_u32 s19, s19, 0x3a00000
	s_sub_u32 s18, s19, 0x2400
	s_add_u32 s20, s19, 0x2400
	s_cmp_eq_u32 s21, 0
	s_cselect_b32 s18, s19, s18
	s_cmpk_eq_u32 s21, 0x7ff
	s_cselect_b32 s20, s19, s20
	buffer_load_dwordx4 v[88:91], v2, s[60:63], s18 offen
	buffer_load_dwordx4 v[92:95], v3, s[60:63], s18 offen
	buffer_load_dwordx4 v[96:99], v2, s[60:63], s19 offen
	buffer_load_dwordx4 v[100:103], v3, s[60:63], s19 offen
	buffer_load_dwordx4 v[104:107], v4, s[60:63], s19 offen
	buffer_load_dwordx4 v[108:111], v2, s[60:63], s20 offen
	buffer_load_dwordx4 v[112:115], v3, s[60:63], s20 offen
	s_add_i32 s10, s10, s16
	s_cmp_lt_u32 s10, 0x4000
	s_cbranch_scc0 .Lcvm_done
	s_branch .Lcvm_loop
.Lcvm_done:
	s_waitcnt vmcnt(0)
.LBB0_175:
	s_or_b64 exec, exec, s[18:19]
	v_readlane_b32 s2, v255, 41
	s_nop 3
	s_cmp_eq_u32 s2, 2
	s_cbranch_scc1 .LBB0_209

; #define PG8_WAIT_V(n) asm volatile("s_waitcnt vmcnt(" #n ")" ::: "memory")
; #define PG8_BAR __builtin_amdgcn_s_barrier()
; template <class Epi, class Sched, bool ALIGN_EPI>
; __device__ __forceinline__ void gemm_phase(PG8_LAS unsigned char* lds, const Gemm g, const Sched& S, const Epi& E) {
;     ...
;     PG8_WAIT_V(0);
;     if constexpr (!ALIGN_EPI) { if (wr == 0) PG8_BAR; }
;     PG8_BAR;
.LBB0_311:
	s_waitcnt vmcnt(0)
	v_readlane_b32 s26, v255, 10
	s_barrier
	v_readlane_b32 s27, v255, 11
	s_branch .Lmcv_entry

; __device__ __forceinline__ int lbid() { int t = blockIdx.x; asm volatile("" : "+s"(t)); return t; }
; __device__ __forceinline__ CArgs get_args() { CArgs p = (CArgs)__builtin_amdgcn_kernarg_segment_ptr(); asm volatile("" : "+s"(p)); return p; }
; __device__ __forceinline__ void xcd_barrier(const XcdBarrier& b) {
;     asm volatile("s_waitcnt vmcnt(0)" ::: "memory");
;     __syncthreads();
;     if (threadIdx.x == 0) {
;         unsigned* bar = b.bar;
;         __builtin_amdgcn_s_waitcnt(0);
;         unsigned nloc = b.st[0], nx = b.st[1];
;         if (nloc == 0u) { xcd_barrier_complete(bar, b.x, nloc, nx); b.st[0] = nloc; b.st[1] = nx; }
; __global__ void __launch_bounds__(NTHR, 2) mk_fwd(Args a_by_value) {
;     ...
;     for (int ph = ph_lo; ph < ph_hi; ++ph) {
;         CArgs a = get_args(); const int bid = lbid();
;         const int layer = ph / PH_PER_LAYER, k = ph % PH_PER_LAYER;
.LBB0_496:
	v_readlane_b32 s2, v253, 1
	s_add_i32 s2, s2, 1
	s_mul_hi_i32 s3, s2, 0x38e38e39
	s_lshr_b32 s6, s3, 31
	s_ashr_i32 s3, s3, 1
	s_add_i32 s3, s3, s6
	s_mul_i32 s3, s3, 9
	s_cmp_eq_u32 s3, s2
	s_cselect_b32 s3, 1, 0
	s_add_i32 s2, s2, s3
	s_nop 1
	s_nop 0
	v_writelane_b32 v253, s2, 1
	s_nop 0
	v_readlane_b32 s3, v253, 2
	s_cmp_ge_i32 s2, s3
	s_cselect_b64 s[6:7], -1, 0
	s_and_b64 vcc, exec, s[6:7]
	s_cbranch_vccnz .LBB0_546
	s_waitcnt vmcnt(0)
	s_waitcnt lgkmcnt(0)
	s_barrier
	s_mov_b64 s[8:9], exec
	v_readlane_b32 s2, v254, 62
	v_readlane_b32 s3, v254, 63
	s_and_b64 s[2:3], s[8:9], s[2:3]
	s_mov_b64 exec, s[2:3]
	s_cbranch_execz .LBB0_545
	v_readlane_b32 s2, v254, 60
	s_waitcnt vmcnt(0) expcnt(0) lgkmcnt(0)
	s_nop 0
	v_mov_b32_e32 v0, s2
	ds_read_b32 v3, v0
	v_readlane_b32 s2, v254, 61
	s_waitcnt lgkmcnt(0)
	v_cmp_ne_u32_e32 vcc, 0, v3
	v_mov_b32_e32 v0, s2
	ds_read_b32 v2, v0
	s_cbranch_vccnz .LBB0_513
	s_mov_b32 s14, 1
	s_branch .LBB0_501

; __device__ __forceinline__ CvtDesc cvt_decode(CArgs a, int layer, int it) {
;     unsigned char* wsw = a->ws + WS_W;
;     constexpr int I_GU = 16 * 176, I_D = 44 * 32, I_IN = 16 * 144, I_UQ = 4 * 24, I_UKV = 2 * 32;
;     CvtDesc d;
;     int r = it;
;     if (r < 2 * I_GU) {
;         const int which = r / I_GU; r -= which * I_GU;
;         const int db = r % 176, kb = r / 176, tile = db >> 3, sub = db & 7;
;         const float* Wg = (which ? a->ffn2_wg : a->ffn1_wg) + (size_t)layer * DM * FF; const float* Wu = (which ? a->ffn2_wu : a->ffn1_wu) + (size_t)layer * DM * FF;
;         d.W = sub < 4 ? Wg : Wu; d.gain = (which ? a->ffn2_norm : a->ffn1_norm) + layer * DM; d.WT = (bf16_t*)(wsw + (which ? W_GU2 : W_GU1));
;         d.N = FF; d.K = DM; d.ld = DM; d.srccol = tile * 128 + (sub & 3) * 32; d.destrow = db * 32; d.k0 = kb * 64; return d;
;     }
;     r -= 2 * I_GU;
;     if (r < 2 * I_D) {
;         const int which = r / I_D; r -= which * I_D;
;         const int db = r % 32, kb = r / 32;
;         d.W = (which ? a->ffn2_wd : a->ffn1_wd) + (size_t)layer * FF * DM; d.gain = nullptr; d.WT = (bf16_t*)(wsw + (which ? W_D2 : W_D1));
;         d.N = DM; d.K = FF; d.ld = HLD; d.srccol = db * 32; d.destrow = db * 32; d.k0 = kb * 64; return d;
;     }
;     r -= 2 * I_D;
;     if (r < I_IN) {
;         const int db = r % 144, kb = r / 144, uc = db * 32;
;         int oc;
;         if (uc < 2560) oc = uc; else if (uc < 2816) oc = 2592 + (uc - 2560); else if (uc < 2944) oc = 2848 + (uc - 2816); else if (uc < 2976) oc = 2976 + (uc - 2944);
;         else if (uc < 3008) oc = 2560 + (uc - 2976); else if (uc < 3072) oc = -1; else oc = 3008 + (uc - 3072);
;         d.W = oc >= 0 ? a->w_in + (size_t)layer * DM * DIN : nullptr; d.gain = a->mix_norm + layer * DM; d.WT = (bf16_t*)(wsw + W_IN);
;         d.N = DIN; d.K = DM; d.ld = DM; d.srccol = oc; d.destrow = uc; d.k0 = kb * 64; return d;
;     }
;     r -= I_IN;
;     if (r < I_UQ) {
;         const int db = r % 24, kb = r / 24;
;         d.W = a->mla_w_uq + (size_t)layer * 256 * 768; d.gain = a->mla_q_norm + layer * 256; d.WT = (bf16_t*)(wsw + W_UQ);
;         d.N = 768; d.K = 256; d.ld = 256; d.srccol = db * 32; d.destrow = db * 32; d.k0 = kb * 64; return d;
;     }
;     r -= I_UQ;
;     if (r < I_UKV) {
;         const int db = r % 32, kb = r / 32, pn = db >> 3, bj = (db & 7) >> 2, wc = db & 3;
.Lmcv_entry:
	v_readlane_b32 s2, v253, 1
	v_readlane_b32 s16, v253, 0
	s_nop 3
	s_mul_hi_i32 s3, s2, 0x38e38e39
	s_lshr_b32 s10, s3, 31
	s_ashr_i32 s3, s3, 1
	s_add_i32 s3, s3, s10
	s_mul_i32 s10, s3, 9
	s_sub_i32 s2, s2, s10
	s_cmp_lt_u32 s16, 0x80
	s_cbranch_scc1 .Lmcv_exit
	s_cmp_eq_u32 s2, 1
	s_cbranch_scc0 .Lmcv_k37
	s_cmp_eq_u32 s3, 0
	s_cbranch_scc1 .Lmcv_exit
	s_mov_b32 s13, 1
	s_mov_b32 s29, s3
	s_movk_i32 s12, 0x1080
	s_branch .Lmcv_go
.Lmcv_k37:
	s_cmp_eq_u32 s3, 3
	s_cbranch_scc1 .Lmcv_exit
	s_add_u32 s29, s3, 1
	s_cmp_eq_u32 s2, 3
	s_cbranch_scc0 .Lmcv_k7
	s_mov_b32 s13, 0
	s_movk_i32 s12, 0x1080
	s_branch .Lmcv_go
.Lmcv_k7:
	s_cmp_eq_u32 s2, 7
	s_cbranch_scc0 .Lmcv_exit
	s_mov_b32 s13, 2
	s_movk_i32 s12, 0xda0
.Lmcv_go:
	s_load_dwordx2 s[88:89], s[6:7], 0xe8
	v_readfirstlane_b32 s2, v244
	v_and_b32_e32 v2, 63, v244
	v_lshrrev_b32_e32 v3, 5, v2
	v_and_b32_e32 v4, 31, v2
	v_lshlrev_b32_e32 v4, 2, v4
	s_lshr_b32 s2, s2, 6
	s_lshl_b32 s3, s2, 14
	v_mul_u32_u24_e32 v5, 0x84, v3
	v_add3_u32 v5, v5, v4, s3
	v_and_b32_e32 v7, 7, v2
	v_lshrrev_b32_e32 v8, 3, v2
	v_mul_u32_u24_e32 v6, 0x420, v7
	v_lshl_add_u32 v6, v8, 2, v6
	v_add_u32_e32 v6, s3, v6
	v_lshlrev_b32_e32 v9, 4, v7
	v_lshlrev_b32_e32 v7, 5, v7
	s_waitcnt lgkmcnt(0)
	s_and_b32 s89, s89, 0xffff
	s_mov_b32 s90, s62
	s_mov_b32 s91, s63
	s_sub_u32 s16, s16, 0x80
	s_lshl_b32 s16, s16, 3
	s_add_u32 s10, s16, s2
	s_movk_i32 s11, 0x400
	s_cmp_lt_u32 s10, s12
	s_cbranch_scc0 .Lmcv_rd_s
	s_mov_b32 s20, 1
	s_cmp_eq_u32 s13, 2
	s_cbranch_scc1 .Lmcv_t2_1
	s_cmpk_lt_u32 s10, 0xb00
	s_cbranch_scc0 .Lmcv_d_1
	s_mul_hi_u32 s2, s10, 0x1745d18
	s_mul_i32 s3, s2, 0xb0
	s_sub_u32 s3, s10, s3
	s_lshr_b32 s48, s3, 3
	s_and_b32 s49, s3, 3
	s_lshl_b32 s50, s48, 7
	s_lshl_b32 s49, s49, 5
	s_add_u32 s50, s50, s49
	s_lshl_b32 s51, s3, 5
	s_lshl_b32 s2, s2, 6
	s_bfe_u32 s3, s3, 0x10002
	s_lshl_b32 s3, s3, 3
	s_cmp_eq_u32 s13, 1
	s_cselect_b32 s17, 0xc8, 24
	s_add_u32 s17, s17, s3
	s_cmp_eq_u32 s13, 1
	s_cselect_b32 s48, 0xc0, 16
	s_mov_b32 s21, 0x600000
	s_cselect_b32 s21, 0x26a0000, s21
	s_mov_b32 s18, 0xb00000
	s_lshl_b32 s49, s29, 12
	s_movk_i32 s23, 0x2c00
	s_movk_i32 s22, 0x800
	s_branch .Lmcv_com_1
.Lmcv_d_1:
	s_sub_u32 s3, s10, 0xb00
	s_and_b32 s50, s3, 31
	s_lshr_b32 s2, s3, 5
	s_lshl_b32 s50, s50, 5
	s_mov_b32 s51, s50
	s_lshl_b32 s2, s2, 6
	s_cmp_eq_u32 s13, 1
	s_cselect_b32 s17, 0xd8, 40
	s_mov_b32 s21, 0x1100000
	s_cselect_b32 s21, 0x31a0000, s21
	s_mov_b32 s18, 0xb00000
	s_mov_b32 s48, -1
	s_mov_b32 s49, 0
	s_movk_i32 s23, 0x1000
	s_movk_i32 s22, 0x2000
	s_mov_b32 s20, 0
	s_branch .Lmcv_com_1
.Lmcv_t2_1:
	s_cmpk_lt_u32 s10, 0x900
	s_cbranch_scc0 .Lmcv_uq_1
	s_mul_hi_u32 s2, s10, 0x1c71c72
	s_mul_i32 s3, s2, 0x90
	s_sub_u32 s3, s10, s3
	s_lshl_b32 s51, s3, 5
	s_lshl_b32 s2, s2, 6
	s_mov_b32 s50, s51
	s_cmpk_lt_u32 s51, 0xa00
	s_cbranch_scc1 .Lmcv_in1_1
	s_add_u32 s50, s51, 32
	s_cmpk_lt_u32 s51, 0xba0
	s_cbranch_scc1 .Lmcv_in1_1
	s_sub_u32 s50, s51, 0x1a0
	s_cmpk_lt_u32 s51, 0xbc0
	s_cbranch_scc1 .Lmcv_in1_1
	s_sub_u32 s50, s51, 64
	s_cmpk_lt_u32 s51, 0xc00
	s_cbranch_scc0 .Lmcv_in1_1
	s_mov_b32 s50, 0
	s_mov_b32 s20, 3
.Lmcv_in1_1:
	s_movk_i32 s17, 56
	s_mov_b32 s18, 0x11c0000
	s_movk_i32 s48, 48
	s_lshl_b32 s49, s29, 12
	s_movk_i32 s23, 0x4700
	s_movk_i32 s22, 0x800
	s_mov_b32 s21, 0x1900000
	s_branch .Lmcv_com_1
.Lmcv_uq_1:
	s_cmpk_lt_u32 s10, 0x960
	s_cbranch_scc0 .Lmcv_ukv_1
	s_sub_u32 s3, s10, 0x900
	s_mul_hi_u32 s2, s3, 0xaaaaaab
	s_mul_i32 s50, s2, 24
	s_sub_u32 s50, s3, s50
	s_lshl_b32 s50, s50, 5
	s_mov_b32 s51, s50
	s_lshl_b32 s2, s2, 6
	s_movk_i32 s17, 120
	s_mov_b32 s18, 0xc0000
	s_movk_i32 s48, 112
	s_lshl_b32 s49, s29, 10
	s_movk_i32 s23, 0xc00
	s_movk_i32 s22, 0x200
	s_mov_b32 s21, 0x2200000
	s_branch .Lmcv_com_1
.Lmcv_ukv_1:
	s_cmpk_lt_u32 s10, 0x9a0
	s_cbranch_scc0 .Lmcv_out_1
	s_sub_u32 s3, s10, 0x960
	s_lshr_b32 s2, s3, 5
	s_and_b32 s3, s3, 31
	s_lshl_b32 s51, s3, 5
	s_lshl_b32 s2, s2, 6
	s_bfe_u32 s50, s3, 0x10003
	s_lshl_b32 s50, s50, 2
	s_and_b32 s49, s3, 3
	s_add_u32 s50, s50, s49
	s_lshl_b32 s50, s50, 7
	s_bfe_u32 s49, s3, 0x10002
	s_lshl_b32 s49, s49, 5
	s_add_u32 s50, s50, s49
	s_bfe_u32 s49, s3, 0x10004
	s_lshl_b32 s49, s49, 6
	s_add_u32 s50, s50, s49
	s_movk_i32 s17, 136
	s_mov_b32 s18, 0x80000
	s_movk_i32 s48, 128
	s_lshl_b32 s49, s29, 9
	s_movk_i32 s23, 0x1000
	s_movk_i32 s22, 0x100
	s_mov_b32 s21, 0x2260000
	s_branch .Lmcv_com_1
.Lmcv_out_1:
	s_sub_u32 s3, s10, 0x9a0
	s_lshr_b32 s2, s3, 5
	s_and_b32 s50, s3, 31
	s_lshl_b32 s50, s50, 5
	s_mov_b32 s51, s50
	s_lshl_b32 s2, s2, 6
	s_movk_i32 s17, 184
	s_mov_b32 s18, 0x800000
	s_movk_i32 s23, 0x1000
	s_movk_i32 s22, 0x1000
	s_mov_b32 s21, 0x22a0000
	s_movk_i32 s48, 104
	s_lshl_b32 s49, s29, 12
	s_cmpk_lt_u32 s2, 0x400
	s_cbranch_scc1 .Lmcv_com_1
	s_movk_i32 s48, 160
	s_lshl_b32 s49, s29, 11
	s_sub_u32 s49, s49, 0x1000
	s_cmpk_lt_u32 s2, 0x600
	s_cbranch_scc1 .Lmcv_com_1
	s_movk_i32 s48, 176
	s_lshl_b32 s49, s29, 11
	s_sub_u32 s49, s49, 0x1800
; __device__ __forceinline__ void cvt_load(const CvtDesc& d, float (&wv)[32], int lane) {
;     if (d.W) {
; #pragma unroll
;         for (int i = 0; i < 32; ++i) { const int kk = 2 * i + (lane >> 5); wv[i] = __builtin_nontemporal_load(d.W + (size_t)(d.k0 + kk) * d.N + d.srccol + (lane & 31)); }
;     } else {
; #pragma unroll
;         for (int i = 0; i < 32; ++i) wv[i] = 0.f;
;     }
; }
; __device__ __forceinline__ void phase_convert(CArgs a, int layer, LAS unsigned char* lds, int G) {
;     ...
;     {
;         int it = gw;
;         float wv[32]; CvtDesc cur;
;         if (it < NIT) { cur = cvt_decode(a, layer, it); cvt_load(cur, wv, lane); }
; #pragma unroll 1
;         while (it < NIT) {
;             const int nxt = it + NGW;
;             float wn[32]; CvtDesc nd = cur;
;             if (nxt < NIT) { nd = cvt_decode(a, layer, nxt); cvt_load(nd, wn, lane); }
;             cvt_store(WSB, cur, wv, scr, lane);
; #pragma unroll
;             for (int i = 0; i < 32; ++i) wv[i] = wn[i];
;             cur = nd; it = nxt;
;         }
.Lmcv_com_1:
	s_load_dwordx2 s[40:41], s[6:7], s17
	s_cmp_eq_u32 s48, -1
	s_cselect_b32 s48, s17, s48
	s_load_dwordx2 s[42:43], s[6:7], s48
	s_mul_i32 s18, s18, s29
	s_mul_i32 s3, s2, s23
	s_lshl_b32 s19, s50, 2
	s_add_u32 s3, s3, s19
	s_add_u32 s18, s18, s3
	s_lshl_b32 s3, s2, 2
	s_cmp_eq_u32 s20, 1
	s_cselect_b32 s49, s49, 0
	s_cselect_b32 s3, s3, 0
	s_add_u32 s49, s49, s3
	s_mul_i32 s3, s51, s22
	s_add_u32 s21, s21, s3
	s_lshl_b32 s3, s2, 1
	s_add_u32 s21, s21, s3
	s_lshl_b32 s28, s23, 1
	s_waitcnt lgkmcnt(0)
	s_add_u32 s44, s40, s18
	s_addc_u32 s45, s41, 0
	s_and_b32 s45, s45, 0xffff
	s_mov_b32 s46, s62
	s_mov_b32 s47, s63
	s_ashr_i32 s3, s49, 31
	s_add_u32 s42, s42, s49
	s_addc_u32 s43, s43, s3
	v_mad_u32_u24 v10, v3, s23, v4
	s_mov_b32 s19, 0
	buffer_load_dword v32, v10, s[44:47], s19 offen nt
	s_add_u32 s19, s19, s28
	buffer_load_dword v33, v10, s[44:47], s19 offen nt
	s_add_u32 s19, s19, s28
	buffer_load_dword v34, v10, s[44:47], s19 offen nt
	s_add_u32 s19, s19, s28
	buffer_load_dword v35, v10, s[44:47], s19 offen nt
	s_add_u32 s19, s19, s28
	buffer_load_dword v36, v10, s[44:47], s19 offen nt
	s_add_u32 s19, s19, s28
	buffer_load_dword v37, v10, s[44:47], s19 offen nt
	s_add_u32 s19, s19, s28
	buffer_load_dword v38, v10, s[44:47], s19 offen nt
	s_add_u32 s19, s19, s28
	buffer_load_dword v39, v10, s[44:47], s19 offen nt
	s_add_u32 s19, s19, s28
	buffer_load_dword v40, v10, s[44:47], s19 offen nt
	s_add_u32 s19, s19, s28
	buffer_load_dword v41, v10, s[44:47], s19 offen nt
	s_add_u32 s19, s19, s28
	buffer_load_dword v42, v10, s[44:47], s19 offen nt
	s_add_u32 s19, s19, s28
	buffer_load_dword v43, v10, s[44:47], s19 offen nt
	s_add_u32 s19, s19, s28
	buffer_load_dword v44, v10, s[44:47], s19 offen nt
	s_add_u32 s19, s19, s28
	buffer_load_dword v45, v10, s[44:47], s19 offen nt
	s_add_u32 s19, s19, s28
	buffer_load_dword v46, v10, s[44:47], s19 offen nt
	s_add_u32 s19, s19, s28
	buffer_load_dword v47, v10, s[44:47], s19 offen nt
	s_add_u32 s19, s19, s28
	buffer_load_dword v48, v10, s[44:47], s19 offen nt
	s_add_u32 s19, s19, s28
	buffer_load_dword v49, v10, s[44:47], s19 offen nt
	s_add_u32 s19, s19, s28
	buffer_load_dword v50, v10, s[44:47], s19 offen nt
	s_add_u32 s19, s19, s28
	buffer_load_dword v51, v10, s[44:47], s19 offen nt
	s_add_u32 s19, s19, s28
	buffer_load_dword v52, v10, s[44:47], s19 offen nt
	s_add_u32 s19, s19, s28
	buffer_load_dword v53, v10, s[44:47], s19 offen nt
	s_add_u32 s19, s19, s28
	buffer_load_dword v54, v10, s[44:47], s19 offen nt
	s_add_u32 s19, s19, s28
	buffer_load_dword v55, v10, s[44:47], s19 offen nt
	s_add_u32 s19, s19, s28
	buffer_load_dword v56, v10, s[44:47], s19 offen nt
	s_add_u32 s19, s19, s28
	buffer_load_dword v57, v10, s[44:47], s19 offen nt
	s_add_u32 s19, s19, s28
	buffer_load_dword v58, v10, s[44:47], s19 offen nt
	s_add_u32 s19, s19, s28
	buffer_load_dword v59, v10, s[44:47], s19 offen nt
	s_add_u32 s19, s19, s28
	buffer_load_dword v60, v10, s[44:47], s19 offen nt
	s_add_u32 s19, s19, s28
	buffer_load_dword v61, v10, s[44:47], s19 offen nt
	s_add_u32 s19, s19, s28
	buffer_load_dword v62, v10, s[44:47], s19 offen nt
	s_add_u32 s19, s19, s28
	buffer_load_dword v63, v10, s[44:47], s19 offen nt
	global_load_dwordx4 v[96:99], v7, s[42:43]
	global_load_dwordx4 v[100:103], v7, s[42:43] offset:16
.Lmcv_loop_s:
	s_add_u32 s16, s10, s11
	s_cmp_lt_u32 s16, s12
	s_cselect_b32 s16, s16, s10
	s_mov_b32 s24, 1
	s_cmp_eq_u32 s13, 2
	s_cbranch_scc1 .Lmcv_t2_2
	s_cmpk_lt_u32 s16, 0xb00
	s_cbranch_scc0 .Lmcv_d_2
	s_mul_hi_u32 s2, s16, 0x1745d18
	s_mul_i32 s3, s2, 0xb0
	s_sub_u32 s3, s16, s3
	s_lshr_b32 s48, s3, 3
	s_and_b32 s49, s3, 3
	s_lshl_b32 s50, s48, 7
	s_lshl_b32 s49, s49, 5
	s_add_u32 s50, s50, s49
	s_lshl_b32 s51, s3, 5
	s_lshl_b32 s2, s2, 6
	s_bfe_u32 s3, s3, 0x10002
	s_lshl_b32 s3, s3, 3
	s_cmp_eq_u32 s13, 1
	s_cselect_b32 s17, 0xc8, 24
	s_add_u32 s17, s17, s3
	s_cmp_eq_u32 s13, 1
	s_cselect_b32 s48, 0xc0, 16
	s_mov_b32 s25, 0x600000
	s_cselect_b32 s25, 0x26a0000, s25
	s_mov_b32 s18, 0xb00000
	s_lshl_b32 s49, s29, 12
	s_movk_i32 s23, 0x2c00
	s_movk_i32 s26, 0x800
	s_branch .Lmcv_com_2
.Lmcv_d_2:
	s_sub_u32 s3, s16, 0xb00
	s_and_b32 s50, s3, 31
	s_lshr_b32 s2, s3, 5
	s_lshl_b32 s50, s50, 5
	s_mov_b32 s51, s50
	s_lshl_b32 s2, s2, 6
	s_cmp_eq_u32 s13, 1
	s_cselect_b32 s17, 0xd8, 40
	s_mov_b32 s25, 0x1100000
	s_cselect_b32 s25, 0x31a0000, s25
	s_mov_b32 s18, 0xb00000
	s_mov_b32 s48, -1
	s_mov_b32 s49, 0
	s_movk_i32 s23, 0x1000
	s_movk_i32 s26, 0x2000
	s_mov_b32 s24, 0
	s_branch .Lmcv_com_2
.Lmcv_t2_2:
	s_cmpk_lt_u32 s16, 0x900
	s_cbranch_scc0 .Lmcv_uq_2
	s_mul_hi_u32 s2, s16, 0x1c71c72
	s_mul_i32 s3, s2, 0x90
	s_sub_u32 s3, s16, s3
	s_lshl_b32 s51, s3, 5
	s_lshl_b32 s2, s2, 6
	s_mov_b32 s50, s51
	s_cmpk_lt_u32 s51, 0xa00
	s_cbranch_scc1 .Lmcv_in1_2
	s_add_u32 s50, s51, 32
	s_cmpk_lt_u32 s51, 0xba0
	s_cbranch_scc1 .Lmcv_in1_2
	s_sub_u32 s50, s51, 0x1a0
	s_cmpk_lt_u32 s51, 0xbc0
	s_cbranch_scc1 .Lmcv_in1_2
	s_sub_u32 s50, s51, 64
	s_cmpk_lt_u32 s51, 0xc00
	s_cbranch_scc0 .Lmcv_in1_2
	s_mov_b32 s50, 0
	s_mov_b32 s24, 3
.Lmcv_in1_2:
	s_movk_i32 s17, 56
	s_mov_b32 s18, 0x11c0000
	s_movk_i32 s48, 48
	s_lshl_b32 s49, s29, 12
	s_movk_i32 s23, 0x4700
	s_movk_i32 s26, 0x800
	s_mov_b32 s25, 0x1900000
	s_branch .Lmcv_com_2
.Lmcv_uq_2:
	s_cmpk_lt_u32 s16, 0x960
	s_cbranch_scc0 .Lmcv_ukv_2
	s_sub_u32 s3, s16, 0x900
	s_mul_hi_u32 s2, s3, 0xaaaaaab
	s_mul_i32 s50, s2, 24
	s_sub_u32 s50, s3, s50
	s_lshl_b32 s50, s50, 5
	s_mov_b32 s51, s50
	s_lshl_b32 s2, s2, 6
	s_movk_i32 s17, 120
	s_mov_b32 s18, 0xc0000
	s_movk_i32 s48, 112
	s_lshl_b32 s49, s29, 10
	s_movk_i32 s23, 0xc00
	s_movk_i32 s26, 0x200
	s_mov_b32 s25, 0x2200000
	s_branch .Lmcv_com_2
; #define LAS __attribute__((address_space(3)))
; __device__ __forceinline__ void cvt_store(const unsigned char* WSB, const CvtDesc& d, const float (&wv)[32], LAS float* scr, int lane) {
; #pragma unroll
;     for (int i = 0; i < 32; ++i) scr[(2 * i + (lane >> 5)) * 33 + (lane & 31)] = wv[i];
;     const int c = lane & 7;
;     float g[8];
;     if (d.gain) { const f32x4 g0 = *(const f32x4*)(d.gain + d.k0 + 8 * c), g1 = *(const f32x4*)(d.gain + d.k0 + 8 * c + 4);
;         g[0] = g0[0]; g[1] = g0[1]; g[2] = g0[2]; g[3] = g0[3]; g[4] = g1[0]; g[5] = g1[1]; g[6] = g1[2]; g[7] = g1[3]; }
;     else {
; #pragma unroll
;         for (int e = 0; e < 8; ++e) g[e] = 1.f;
;     }
;     asm volatile("s_waitcnt lgkmcnt(0)" ::: "memory");
; __device__ __forceinline__ CvtDesc cvt_decode(CArgs a, int layer, int it) {
;     ...
;     if (r < I_UQ) {
;         const int db = r % 24, kb = r / 24;
;         d.W = a->mla_w_uq + (size_t)layer * 256 * 768; d.gain = a->mla_q_norm + layer * 256; d.WT = (bf16_t*)(wsw + W_UQ);
;         d.N = 768; d.K = 256; d.ld = 256; d.srccol = db * 32; d.destrow = db * 32; d.k0 = kb * 64; return d;
;     }
;     r -= I_UQ;
;     if (r < I_UKV) {
;         const int db = r % 32, kb = r / 32, pn = db >> 3, bj = (db & 7) >> 2, wc = db & 3;
;         d.W = a->mla_w_ukv + (size_t)layer * 128 * 1024; d.gain = a->mla_kv_norm + layer * 128; d.WT = (bf16_t*)(wsw + W_UKV);
;         d.N = 1024; d.K = 128; d.ld = 128; d.srccol = (pn < 2) ? (4 * pn + wc) * 128 + 32 * bj : (4 * (pn - 2) + wc) * 128 + 64 + 32 * bj; d.destrow = db * 32; d.k0 = kb * 64; return d;
;     }
;     r -= I_UKV;
;     {
;         const int db = r % 32, kb = r / 32, k0 = kb * 64;
;         d.W = a->w_out + (size_t)layer * 2048 * DM;
;         d.gain = (k0 < 1024) ? a->ssd_norm + layer * 1024 : (k0 < 1536) ? a->mla_out_norm + layer * 512 - 1024 : a->conv_out_norm + layer * 512 - 1536;
;         d.WT = (bf16_t*)(wsw + W_OUT); d.N = DM; d.K = 2048; d.ld = 2048; d.srccol = db * 32; d.destrow = db * 32; d.k0 = k0; return d;
;     }
.Lmcv_ukv_2:
	s_cmpk_lt_u32 s16, 0x9a0
	s_cbranch_scc0 .Lmcv_out_2
	s_sub_u32 s3, s16, 0x960
	s_lshr_b32 s2, s3, 5
	s_and_b32 s3, s3, 31
	s_lshl_b32 s51, s3, 5
	s_lshl_b32 s2, s2, 6
	s_bfe_u32 s50, s3, 0x10003
	s_lshl_b32 s50, s50, 2
	s_and_b32 s49, s3, 3
	s_add_u32 s50, s50, s49
	s_lshl_b32 s50, s50, 7
	s_bfe_u32 s49, s3, 0x10002
	s_lshl_b32 s49, s49, 5
	s_add_u32 s50, s50, s49
	s_bfe_u32 s49, s3, 0x10004
	s_lshl_b32 s49, s49, 6
	s_add_u32 s50, s50, s49
	s_movk_i32 s17, 136
	s_mov_b32 s18, 0x80000
	s_movk_i32 s48, 128
	s_lshl_b32 s49, s29, 9
	s_movk_i32 s23, 0x1000
	s_movk_i32 s26, 0x100
	s_mov_b32 s25, 0x2260000
	s_branch .Lmcv_com_2
.Lmcv_out_2:
	s_sub_u32 s3, s16, 0x9a0
	s_lshr_b32 s2, s3, 5
	s_and_b32 s50, s3, 31
	s_lshl_b32 s50, s50, 5
	s_mov_b32 s51, s50
	s_lshl_b32 s2, s2, 6
	s_movk_i32 s17, 184
	s_mov_b32 s18, 0x800000
	s_movk_i32 s23, 0x1000
	s_movk_i32 s26, 0x1000
	s_mov_b32 s25, 0x22a0000
	s_movk_i32 s48, 104
	s_lshl_b32 s49, s29, 12
	s_cmpk_lt_u32 s2, 0x400
	s_cbranch_scc1 .Lmcv_com_2
	s_movk_i32 s48, 160
	s_lshl_b32 s49, s29, 11
	s_sub_u32 s49, s49, 0x1000
	s_cmpk_lt_u32 s2, 0x600
	s_cbranch_scc1 .Lmcv_com_2
	s_movk_i32 s48, 176
	s_lshl_b32 s49, s29, 11
	s_sub_u32 s49, s49, 0x1800
.Lmcv_com_2:
	s_load_dwordx2 s[40:41], s[6:7], s17
	s_cmp_eq_u32 s48, -1
	s_cselect_b32 s48, s17, s48
	s_load_dwordx2 s[42:43], s[6:7], s48
	s_mul_i32 s18, s18, s29
	s_mul_i32 s3, s2, s23
	s_lshl_b32 s19, s50, 2
	s_add_u32 s3, s3, s19
	s_add_u32 s18, s18, s3
	s_lshl_b32 s3, s2, 2
	s_cmp_eq_u32 s24, 1
	s_cselect_b32 s49, s49, 0
	s_cselect_b32 s3, s3, 0
	s_add_u32 s49, s49, s3
	s_mul_i32 s3, s51, s26
	s_add_u32 s25, s25, s3
	s_lshl_b32 s3, s2, 1
	s_add_u32 s25, s25, s3
	s_lshl_b32 s28, s23, 1
	s_waitcnt lgkmcnt(0)
	s_add_u32 s44, s40, s18
	s_addc_u32 s45, s41, 0
	s_and_b32 s45, s45, 0xffff
	s_mov_b32 s46, s62
	s_mov_b32 s47, s63
	s_ashr_i32 s3, s49, 31
	s_add_u32 s42, s42, s49
	s_addc_u32 s43, s43, s3
	v_mad_u32_u24 v10, v3, s23, v4
	s_mov_b32 s19, 0
	buffer_load_dword v64, v10, s[44:47], s19 offen nt
	s_add_u32 s19, s19, s28
	buffer_load_dword v65, v10, s[44:47], s19 offen nt
	s_add_u32 s19, s19, s28
	buffer_load_dword v66, v10, s[44:47], s19 offen nt
	s_add_u32 s19, s19, s28
	buffer_load_dword v67, v10, s[44:47], s19 offen nt
	s_add_u32 s19, s19, s28
	buffer_load_dword v68, v10, s[44:47], s19 offen nt
	s_add_u32 s19, s19, s28
	buffer_load_dword v69, v10, s[44:47], s19 offen nt
	s_add_u32 s19, s19, s28
	buffer_load_dword v70, v10, s[44:47], s19 offen nt
	s_add_u32 s19, s19, s28
	buffer_load_dword v71, v10, s[44:47], s19 offen nt
	s_add_u32 s19, s19, s28
	buffer_load_dword v72, v10, s[44:47], s19 offen nt
	s_add_u32 s19, s19, s28
	buffer_load_dword v73, v10, s[44:47], s19 offen nt
	s_add_u32 s19, s19, s28
	buffer_load_dword v74, v10, s[44:47], s19 offen nt
	s_add_u32 s19, s19, s28
	buffer_load_dword v75, v10, s[44:47], s19 offen nt
	s_add_u32 s19, s19, s28
	buffer_load_dword v76, v10, s[44:47], s19 offen nt
	s_add_u32 s19, s19, s28
	buffer_load_dword v77, v10, s[44:47], s19 offen nt
	s_add_u32 s19, s19, s28
	buffer_load_dword v78, v10, s[44:47], s19 offen nt
	s_add_u32 s19, s19, s28
	buffer_load_dword v79, v10, s[44:47], s19 offen nt
	s_add_u32 s19, s19, s28
	buffer_load_dword v80, v10, s[44:47], s19 offen nt
	s_add_u32 s19, s19, s28
	buffer_load_dword v81, v10, s[44:47], s19 offen nt
	s_add_u32 s19, s19, s28
	buffer_load_dword v82, v10, s[44:47], s19 offen nt
	s_add_u32 s19, s19, s28
	buffer_load_dword v83, v10, s[44:47], s19 offen nt
	s_add_u32 s19, s19, s28
	buffer_load_dword v84, v10, s[44:47], s19 offen nt
	s_add_u32 s19, s19, s28
	buffer_load_dword v85, v10, s[44:47], s19 offen nt
	s_add_u32 s19, s19, s28
	buffer_load_dword v86, v10, s[44:47], s19 offen nt
	s_add_u32 s19, s19, s28
	buffer_load_dword v87, v10, s[44:47], s19 offen nt
	s_add_u32 s19, s19, s28
	buffer_load_dword v88, v10, s[44:47], s19 offen nt
	s_add_u32 s19, s19, s28
	buffer_load_dword v89, v10, s[44:47], s19 offen nt
	s_add_u32 s19, s19, s28
	buffer_load_dword v90, v10, s[44:47], s19 offen nt
	s_add_u32 s19, s19, s28
	buffer_load_dword v91, v10, s[44:47], s19 offen nt
	s_add_u32 s19, s19, s28
	buffer_load_dword v92, v10, s[44:47], s19 offen nt
	s_add_u32 s19, s19, s28
	buffer_load_dword v93, v10, s[44:47], s19 offen nt
	s_add_u32 s19, s19, s28
	buffer_load_dword v94, v10, s[44:47], s19 offen nt
	s_add_u32 s19, s19, s28
	buffer_load_dword v95, v10, s[44:47], s19 offen nt
	global_load_dwordx4 v[104:107], v7, s[42:43]
	global_load_dwordx4 v[108:111], v7, s[42:43] offset:16
	s_waitcnt vmcnt(34)
	ds_write_b32 v5, v32 offset:0
	ds_write_b32 v5, v33 offset:264
	ds_write_b32 v5, v34 offset:528
	ds_write_b32 v5, v35 offset:792
	ds_write_b32 v5, v36 offset:1056
	ds_write_b32 v5, v37 offset:1320
	ds_write_b32 v5, v38 offset:1584
	ds_write_b32 v5, v39 offset:1848
	ds_write_b32 v5, v40 offset:2112
	ds_write_b32 v5, v41 offset:2376
	ds_write_b32 v5, v42 offset:2640
	ds_write_b32 v5, v43 offset:2904
	ds_write_b32 v5, v44 offset:3168
	ds_write_b32 v5, v45 offset:3432
	ds_write_b32 v5, v46 offset:3696
	ds_write_b32 v5, v47 offset:3960
	ds_write_b32 v5, v48 offset:4224
	ds_write_b32 v5, v49 offset:4488
	ds_write_b32 v5, v50 offset:4752
	ds_write_b32 v5, v51 offset:5016
	ds_write_b32 v5, v52 offset:5280
	ds_write_b32 v5, v53 offset:5544
	ds_write_b32 v5, v54 offset:5808
	ds_write_b32 v5, v55 offset:6072
	ds_write_b32 v5, v56 offset:6336
	ds_write_b32 v5, v57 offset:6600
	ds_write_b32 v5, v58 offset:6864
	ds_write_b32 v5, v59 offset:7128
	ds_write_b32 v5, v60 offset:7392
	ds_write_b32 v5, v61 offset:7656
	ds_write_b32 v5, v62 offset:7920
	ds_write_b32 v5, v63 offset:8184
	s_bitcmp1_b32 s20, 0
	s_cbranch_scc1 .Lmcv_hg_3
	v_mov_b32_e32 v96, 1.0
	v_mov_b32_e32 v97, 1.0
	v_mov_b32_e32 v98, 1.0
	v_mov_b32_e32 v99, 1.0
	v_mov_b32_e32 v100, 1.0
	v_mov_b32_e32 v101, 1.0
	v_mov_b32_e32 v102, 1.0
	v_mov_b32_e32 v103, 1.0
; #define wt16(p, v) wt16b(WSB, (p), (v))
; #define LAS __attribute__((address_space(3)))
; __device__ __forceinline__ void cvt_store(const unsigned char* WSB, const CvtDesc& d, const float (&wv)[32], LAS float* scr, int lane) {
;     ...
; #pragma unroll
;     for (int j = 0; j < 4; ++j) { const int n = (lane >> 3) + 8 * j; const LAS float* sp = scr + (8 * c) * 33 + n;
;         u32x4 o; o.x = cvt_pk_bf16(sp[0 * 33] * g[0], sp[1 * 33] * g[1]); o.y = cvt_pk_bf16(sp[2 * 33] * g[2], sp[3 * 33] * g[3]);
;         o.z = cvt_pk_bf16(sp[4 * 33] * g[4], sp[5 * 33] * g[5]); o.w = cvt_pk_bf16(sp[6 * 33] * g[6], sp[7 * 33] * g[7]);
;         wt16(d.WT + (size_t)(d.destrow + n) * d.ld + d.k0 + 8 * c, o); }
;     asm volatile("s_waitcnt lgkmcnt(0)" ::: "memory");
; }
; __device__ __forceinline__ CvtDesc cvt_decode(CArgs a, int layer, int it) {
;     ...
;     if (r < 2 * I_GU) {
;         const int which = r / I_GU; r -= which * I_GU;
;         const int db = r % 176, kb = r / 176, tile = db >> 3, sub = db & 7;
;         const float* Wg = (which ? a->ffn2_wg : a->ffn1_wg) + (size_t)layer * DM * FF; const float* Wu = (which ? a->ffn2_wu : a->ffn1_wu) + (size_t)layer * DM * FF;
;         d.W = sub < 4 ? Wg : Wu; d.gain = (which ? a->ffn2_norm : a->ffn1_norm) + layer * DM; d.WT = (bf16_t*)(wsw + (which ? W_GU2 : W_GU1));
;         d.N = FF; d.K = DM; d.ld = DM; d.srccol = tile * 128 + (sub & 3) * 32; d.destrow = db * 32; d.k0 = kb * 64; return d;
;     }
;     r -= 2 * I_GU;
;     if (r < 2 * I_D) {
;         const int which = r / I_D; r -= which * I_D;
;         const int db = r % 32, kb = r / 32;
;         d.W = (which ? a->ffn2_wd : a->ffn1_wd) + (size_t)layer * FF * DM; d.gain = nullptr; d.WT = (bf16_t*)(wsw + (which ? W_D2 : W_D1));
;         d.N = DM; d.K = FF; d.ld = HLD; d.srccol = db * 32; d.destrow = db * 32; d.k0 = kb * 64; return d;
;     }
;     r -= 2 * I_D;
;     if (r < I_IN) {
;         const int db = r % 144, kb = r / 144, uc = db * 32;
;         int oc;
;         if (uc < 2560) oc = uc; else if (uc < 2816) oc = 2592 + (uc - 2560); else if (uc < 2944) oc = 2848 + (uc - 2816); else if (uc < 2976) oc = 2976 + (uc - 2944);
;         else if (uc < 3008) oc = 2560 + (uc - 2976); else if (uc < 3072) oc = -1; else oc = 3008 + (uc - 3072);
;         d.W = oc >= 0 ? a->w_in + (size_t)layer * DM * DIN : nullptr; d.gain = a->mix_norm + layer * DM; d.WT = (bf16_t*)(wsw + W_IN);
.Lmcv_hg_3:
	v_mad_u32_u24 v11, v8, s22, v9
	s_waitcnt lgkmcnt(0)
	ds_read_b32 v112, v6 offset:0
	ds_read_b32 v113, v6 offset:132
	ds_read_b32 v114, v6 offset:264
	ds_read_b32 v115, v6 offset:396
	ds_read_b32 v116, v6 offset:528
	ds_read_b32 v117, v6 offset:660
	ds_read_b32 v118, v6 offset:792
	ds_read_b32 v119, v6 offset:924
	ds_read_b32 v120, v6 offset:32
	ds_read_b32 v121, v6 offset:164
	ds_read_b32 v122, v6 offset:296
	ds_read_b32 v123, v6 offset:428
	ds_read_b32 v124, v6 offset:560
	ds_read_b32 v125, v6 offset:692
	ds_read_b32 v126, v6 offset:824
	ds_read_b32 v127, v6 offset:956
	ds_read_b32 v128, v6 offset:64
	ds_read_b32 v129, v6 offset:196
	ds_read_b32 v130, v6 offset:328
	ds_read_b32 v131, v6 offset:460
	ds_read_b32 v132, v6 offset:592
	ds_read_b32 v133, v6 offset:724
	ds_read_b32 v134, v6 offset:856
	ds_read_b32 v135, v6 offset:988
	ds_read_b32 v136, v6 offset:96
	ds_read_b32 v137, v6 offset:228
	ds_read_b32 v138, v6 offset:360
	ds_read_b32 v139, v6 offset:492
	ds_read_b32 v140, v6 offset:624
	ds_read_b32 v141, v6 offset:756
	ds_read_b32 v142, v6 offset:888
	ds_read_b32 v143, v6 offset:1020
	s_waitcnt lgkmcnt(0)
	v_mul_f32_e32 v112, v112, v96
	v_mul_f32_e32 v113, v113, v97
	v_mul_f32_e32 v114, v114, v98
	v_mul_f32_e32 v115, v115, v99
	v_mul_f32_e32 v116, v116, v100
	v_mul_f32_e32 v117, v117, v101
	v_mul_f32_e32 v118, v118, v102
	v_mul_f32_e32 v119, v119, v103
	v_mul_f32_e32 v120, v120, v96
	v_mul_f32_e32 v121, v121, v97
	v_mul_f32_e32 v122, v122, v98
	v_mul_f32_e32 v123, v123, v99
	v_mul_f32_e32 v124, v124, v100
	v_mul_f32_e32 v125, v125, v101
	v_mul_f32_e32 v126, v126, v102
	v_mul_f32_e32 v127, v127, v103
	v_mul_f32_e32 v128, v128, v96
	v_mul_f32_e32 v129, v129, v97
	v_mul_f32_e32 v130, v130, v98
	v_mul_f32_e32 v131, v131, v99
	v_mul_f32_e32 v132, v132, v100
	v_mul_f32_e32 v133, v133, v101
	v_mul_f32_e32 v134, v134, v102
	v_mul_f32_e32 v135, v135, v103
	v_mul_f32_e32 v136, v136, v96
	v_mul_f32_e32 v137, v137, v97
	v_mul_f32_e32 v138, v138, v98
	v_mul_f32_e32 v139, v139, v99
	v_mul_f32_e32 v140, v140, v100
	v_mul_f32_e32 v141, v141, v101
	v_mul_f32_e32 v142, v142, v102
	v_mul_f32_e32 v143, v143, v103
	s_bitcmp1_b32 s20, 1
	s_cbranch_scc0 .Lmcv_np_3
	v_mov_b32_e32 v112, 0
	v_mov_b32_e32 v113, 0
	v_mov_b32_e32 v114, 0
	v_mov_b32_e32 v115, 0
	v_mov_b32_e32 v116, 0
	v_mov_b32_e32 v117, 0
	v_mov_b32_e32 v118, 0
	v_mov_b32_e32 v119, 0
	v_mov_b32_e32 v120, 0
	v_mov_b32_e32 v121, 0
	v_mov_b32_e32 v122, 0
	v_mov_b32_e32 v123, 0
	v_mov_b32_e32 v124, 0
	v_mov_b32_e32 v125, 0
	v_mov_b32_e32 v126, 0
	v_mov_b32_e32 v127, 0
	v_mov_b32_e32 v128, 0
	v_mov_b32_e32 v129, 0
	v_mov_b32_e32 v130, 0
	v_mov_b32_e32 v131, 0
	v_mov_b32_e32 v132, 0
	v_mov_b32_e32 v133, 0
	v_mov_b32_e32 v134, 0
	v_mov_b32_e32 v135, 0
	v_mov_b32_e32 v136, 0
	v_mov_b32_e32 v137, 0
	v_mov_b32_e32 v138, 0
	v_mov_b32_e32 v139, 0
	v_mov_b32_e32 v140, 0
	v_mov_b32_e32 v141, 0
	v_mov_b32_e32 v142, 0
	v_mov_b32_e32 v143, 0
.Lmcv_np_3:
	s_lshl_b32 s3, s22, 3
	v_cvt_pk_bf16_f32 v144, v112, v113
	v_cvt_pk_bf16_f32 v145, v114, v115
	v_cvt_pk_bf16_f32 v146, v116, v117
	v_cvt_pk_bf16_f32 v147, v118, v119
	buffer_store_dwordx4 v[144:147], v11, s[88:91], s21 offen sc1
	s_add_u32 s21, s21, s3
	s_nop 0
	v_cvt_pk_bf16_f32 v144, v120, v121
	v_cvt_pk_bf16_f32 v145, v122, v123
	v_cvt_pk_bf16_f32 v146, v124, v125
	v_cvt_pk_bf16_f32 v147, v126, v127
	buffer_store_dwordx4 v[144:147], v11, s[88:91], s21 offen sc1
	s_add_u32 s21, s21, s3
	s_nop 0
	v_cvt_pk_bf16_f32 v144, v128, v129
	v_cvt_pk_bf16_f32 v145, v130, v131
	v_cvt_pk_bf16_f32 v146, v132, v133
	v_cvt_pk_bf16_f32 v147, v134, v135
	buffer_store_dwordx4 v[144:147], v11, s[88:91], s21 offen sc1
	s_add_u32 s21, s21, s3
	s_nop 0
	v_cvt_pk_bf16_f32 v144, v136, v137
	v_cvt_pk_bf16_f32 v145, v138, v139
	v_cvt_pk_bf16_f32 v146, v140, v141
	v_cvt_pk_bf16_f32 v147, v142, v143
	buffer_store_dwordx4 v[144:147], v11, s[88:91], s21 offen sc1
	s_add_u32 s10, s10, s11
	s_cmp_lt_u32 s10, s12
	s_cbranch_scc0 .Lmcv_rd_s
	s_add_u32 s16, s10, s11
	s_cmp_lt_u32 s16, s12
	s_cselect_b32 s16, s16, s10
	s_mov_b32 s20, 1
	s_cmp_eq_u32 s13, 2
	s_cbranch_scc1 .Lmcv_t2_4
	s_cmpk_lt_u32 s16, 0xb00
	s_cbranch_scc0 .Lmcv_d_4
	s_mul_hi_u32 s2, s16, 0x1745d18
	s_mul_i32 s3, s2, 0xb0
	s_sub_u32 s3, s16, s3
	s_lshr_b32 s48, s3, 3
	s_and_b32 s49, s3, 3
	s_lshl_b32 s50, s48, 7
	s_lshl_b32 s49, s49, 5
	s_add_u32 s50, s50, s49
	s_lshl_b32 s51, s3, 5
	s_lshl_b32 s2, s2, 6
	s_bfe_u32 s3, s3, 0x10002
	s_lshl_b32 s3, s3, 3
	s_cmp_eq_u32 s13, 1
	s_cselect_b32 s17, 0xc8, 24
	s_add_u32 s17, s17, s3
	s_cmp_eq_u32 s13, 1
	s_cselect_b32 s48, 0xc0, 16
	s_mov_b32 s21, 0x600000
	s_cselect_b32 s21, 0x26a0000, s21
	s_mov_b32 s18, 0xb00000
	s_lshl_b32 s49, s29, 12
	s_movk_i32 s23, 0x2c00
	s_movk_i32 s22, 0x800
	s_branch .Lmcv_com_4
.Lmcv_d_4:
	s_sub_u32 s3, s16, 0xb00
	s_and_b32 s50, s3, 31
	s_lshr_b32 s2, s3, 5
	s_lshl_b32 s50, s50, 5
	s_mov_b32 s51, s50
	s_lshl_b32 s2, s2, 6
	s_cmp_eq_u32 s13, 1
	s_cselect_b32 s17, 0xd8, 40
	s_mov_b32 s21, 0x1100000
	s_cselect_b32 s21, 0x31a0000, s21
	s_mov_b32 s18, 0xb00000
	s_mov_b32 s48, -1
	s_mov_b32 s49, 0
	s_movk_i32 s23, 0x1000
	s_movk_i32 s22, 0x2000
	s_mov_b32 s20, 0
	s_branch .Lmcv_com_4
.Lmcv_t2_4:
	s_cmpk_lt_u32 s16, 0x900
	s_cbranch_scc0 .Lmcv_uq_4
	s_mul_hi_u32 s2, s16, 0x1c71c72
	s_mul_i32 s3, s2, 0x90
	s_sub_u32 s3, s16, s3
	s_lshl_b32 s51, s3, 5
	s_lshl_b32 s2, s2, 6
	s_mov_b32 s50, s51
	s_cmpk_lt_u32 s51, 0xa00
	s_cbranch_scc1 .Lmcv_in1_4
	s_add_u32 s50, s51, 32
	s_cmpk_lt_u32 s51, 0xba0
	s_cbranch_scc1 .Lmcv_in1_4
	s_sub_u32 s50, s51, 0x1a0
	s_cmpk_lt_u32 s51, 0xbc0
	s_cbranch_scc1 .Lmcv_in1_4
	s_sub_u32 s50, s51, 64
	s_cmpk_lt_u32 s51, 0xc00
	s_cbranch_scc0 .Lmcv_in1_4
	s_mov_b32 s50, 0
	s_mov_b32 s20, 3

; #define LAS __attribute__((address_space(3)))
; __device__ __forceinline__ void cvt_load(const CvtDesc& d, float (&wv)[32], int lane) {
;     if (d.W) {
; #pragma unroll
;         for (int i = 0; i < 32; ++i) { const int kk = 2 * i + (lane >> 5); wv[i] = __builtin_nontemporal_load(d.W + (size_t)(d.k0 + kk) * d.N + d.srccol + (lane & 31)); }
;     } else {
; #pragma unroll
;         for (int i = 0; i < 32; ++i) wv[i] = 0.f;
;     }
; }
; __device__ __forceinline__ void cvt_store(const unsigned char* WSB, const CvtDesc& d, const float (&wv)[32], LAS float* scr, int lane) {
; #pragma unroll
;     for (int i = 0; i < 32; ++i) scr[(2 * i + (lane >> 5)) * 33 + (lane & 31)] = wv[i];
;     const int c = lane & 7;
;     float g[8];
;     if (d.gain) { const f32x4 g0 = *(const f32x4*)(d.gain + d.k0 + 8 * c), g1 = *(const f32x4*)(d.gain + d.k0 + 8 * c + 4);
;         g[0] = g0[0]; g[1] = g0[1]; g[2] = g0[2]; g[3] = g0[3]; g[4] = g1[0]; g[5] = g1[1]; g[6] = g1[2]; g[7] = g1[3]; }
;     else {
; #pragma unroll
;         for (int e = 0; e < 8; ++e) g[e] = 1.f;
;     }
;     asm volatile("s_waitcnt lgkmcnt(0)" ::: "memory");
.Lmcv_uq_4:
	s_cmpk_lt_u32 s16, 0x960
	s_cbranch_scc0 .Lmcv_ukv_4
	s_sub_u32 s3, s16, 0x900
	s_mul_hi_u32 s2, s3, 0xaaaaaab
	s_mul_i32 s50, s2, 24
	s_sub_u32 s50, s3, s50
	s_lshl_b32 s50, s50, 5
	s_mov_b32 s51, s50
	s_lshl_b32 s2, s2, 6
	s_movk_i32 s17, 120
	s_mov_b32 s18, 0xc0000
	s_movk_i32 s48, 112
	s_lshl_b32 s49, s29, 10
	s_movk_i32 s23, 0xc00
	s_movk_i32 s22, 0x200
	s_mov_b32 s21, 0x2200000
	s_branch .Lmcv_com_4
.Lmcv_ukv_4:
	s_cmpk_lt_u32 s16, 0x9a0
	s_cbranch_scc0 .Lmcv_out_4
	s_sub_u32 s3, s16, 0x960
	s_lshr_b32 s2, s3, 5
	s_and_b32 s3, s3, 31
	s_lshl_b32 s51, s3, 5
	s_lshl_b32 s2, s2, 6
	s_bfe_u32 s50, s3, 0x10003
	s_lshl_b32 s50, s50, 2
	s_and_b32 s49, s3, 3
	s_add_u32 s50, s50, s49
	s_lshl_b32 s50, s50, 7
	s_bfe_u32 s49, s3, 0x10002
	s_lshl_b32 s49, s49, 5
	s_add_u32 s50, s50, s49
	s_bfe_u32 s49, s3, 0x10004
	s_lshl_b32 s49, s49, 6
	s_add_u32 s50, s50, s49
	s_movk_i32 s17, 136
	s_mov_b32 s18, 0x80000
	s_movk_i32 s48, 128
	s_lshl_b32 s49, s29, 9
	s_movk_i32 s23, 0x1000
	s_movk_i32 s22, 0x100
	s_mov_b32 s21, 0x2260000
	s_branch .Lmcv_com_4
.Lmcv_out_4:
	s_sub_u32 s3, s16, 0x9a0
	s_lshr_b32 s2, s3, 5
	s_and_b32 s50, s3, 31
	s_lshl_b32 s50, s50, 5
	s_mov_b32 s51, s50
	s_lshl_b32 s2, s2, 6
	s_movk_i32 s17, 184
	s_mov_b32 s18, 0x800000
	s_movk_i32 s23, 0x1000
	s_movk_i32 s22, 0x1000
	s_mov_b32 s21, 0x22a0000
	s_movk_i32 s48, 104
	s_lshl_b32 s49, s29, 12
	s_cmpk_lt_u32 s2, 0x400
	s_cbranch_scc1 .Lmcv_com_4
	s_movk_i32 s48, 160
	s_lshl_b32 s49, s29, 11
	s_sub_u32 s49, s49, 0x1000
	s_cmpk_lt_u32 s2, 0x600
	s_cbranch_scc1 .Lmcv_com_4
	s_movk_i32 s48, 176
	s_lshl_b32 s49, s29, 11
	s_sub_u32 s49, s49, 0x1800
.Lmcv_com_4:
	s_load_dwordx2 s[40:41], s[6:7], s17
	s_cmp_eq_u32 s48, -1
	s_cselect_b32 s48, s17, s48
	s_load_dwordx2 s[42:43], s[6:7], s48
	s_mul_i32 s18, s18, s29
	s_mul_i32 s3, s2, s23
	s_lshl_b32 s19, s50, 2
	s_add_u32 s3, s3, s19
	s_add_u32 s18, s18, s3
	s_lshl_b32 s3, s2, 2
	s_cmp_eq_u32 s20, 1
	s_cselect_b32 s49, s49, 0
	s_cselect_b32 s3, s3, 0
	s_add_u32 s49, s49, s3
	s_mul_i32 s3, s51, s22
	s_add_u32 s21, s21, s3
	s_lshl_b32 s3, s2, 1
	s_add_u32 s21, s21, s3
	s_lshl_b32 s28, s23, 1
	s_waitcnt lgkmcnt(0)
	s_add_u32 s44, s40, s18
	s_addc_u32 s45, s41, 0
	s_and_b32 s45, s45, 0xffff
	s_mov_b32 s46, s62
	s_mov_b32 s47, s63
	s_ashr_i32 s3, s49, 31
	s_add_u32 s42, s42, s49
	s_addc_u32 s43, s43, s3
	v_mad_u32_u24 v10, v3, s23, v4
	s_mov_b32 s19, 0
	buffer_load_dword v32, v10, s[44:47], s19 offen nt
	s_add_u32 s19, s19, s28
	buffer_load_dword v33, v10, s[44:47], s19 offen nt
	s_add_u32 s19, s19, s28
	buffer_load_dword v34, v10, s[44:47], s19 offen nt
	s_add_u32 s19, s19, s28
	buffer_load_dword v35, v10, s[44:47], s19 offen nt
	s_add_u32 s19, s19, s28
	buffer_load_dword v36, v10, s[44:47], s19 offen nt
	s_add_u32 s19, s19, s28
	buffer_load_dword v37, v10, s[44:47], s19 offen nt
	s_add_u32 s19, s19, s28
	buffer_load_dword v38, v10, s[44:47], s19 offen nt
	s_add_u32 s19, s19, s28
	buffer_load_dword v39, v10, s[44:47], s19 offen nt
	s_add_u32 s19, s19, s28
	buffer_load_dword v40, v10, s[44:47], s19 offen nt
	s_add_u32 s19, s19, s28
	buffer_load_dword v41, v10, s[44:47], s19 offen nt
	s_add_u32 s19, s19, s28
	buffer_load_dword v42, v10, s[44:47], s19 offen nt
	s_add_u32 s19, s19, s28
	buffer_load_dword v43, v10, s[44:47], s19 offen nt
	s_add_u32 s19, s19, s28
	buffer_load_dword v44, v10, s[44:47], s19 offen nt
	s_add_u32 s19, s19, s28
	buffer_load_dword v45, v10, s[44:47], s19 offen nt
	s_add_u32 s19, s19, s28
	buffer_load_dword v46, v10, s[44:47], s19 offen nt
	s_add_u32 s19, s19, s28
	buffer_load_dword v47, v10, s[44:47], s19 offen nt
	s_add_u32 s19, s19, s28
	buffer_load_dword v48, v10, s[44:47], s19 offen nt
	s_add_u32 s19, s19, s28
	buffer_load_dword v49, v10, s[44:47], s19 offen nt
	s_add_u32 s19, s19, s28
	buffer_load_dword v50, v10, s[44:47], s19 offen nt
	s_add_u32 s19, s19, s28
	buffer_load_dword v51, v10, s[44:47], s19 offen nt
	s_add_u32 s19, s19, s28
	buffer_load_dword v52, v10, s[44:47], s19 offen nt
	s_add_u32 s19, s19, s28
	buffer_load_dword v53, v10, s[44:47], s19 offen nt
	s_add_u32 s19, s19, s28
	buffer_load_dword v54, v10, s[44:47], s19 offen nt
	s_add_u32 s19, s19, s28
	buffer_load_dword v55, v10, s[44:47], s19 offen nt
	s_add_u32 s19, s19, s28
	buffer_load_dword v56, v10, s[44:47], s19 offen nt
	s_add_u32 s19, s19, s28
	buffer_load_dword v57, v10, s[44:47], s19 offen nt
	s_add_u32 s19, s19, s28
	buffer_load_dword v58, v10, s[44:47], s19 offen nt
	s_add_u32 s19, s19, s28
	buffer_load_dword v59, v10, s[44:47], s19 offen nt
	s_add_u32 s19, s19, s28
	buffer_load_dword v60, v10, s[44:47], s19 offen nt
	s_add_u32 s19, s19, s28
	buffer_load_dword v61, v10, s[44:47], s19 offen nt
	s_add_u32 s19, s19, s28
	buffer_load_dword v62, v10, s[44:47], s19 offen nt
	s_add_u32 s19, s19, s28
	buffer_load_dword v63, v10, s[44:47], s19 offen nt
	global_load_dwordx4 v[96:99], v7, s[42:43]
	global_load_dwordx4 v[100:103], v7, s[42:43] offset:16
	s_waitcnt vmcnt(34)
	ds_write_b32 v5, v64 offset:0
	ds_write_b32 v5, v65 offset:264
	ds_write_b32 v5, v66 offset:528
	ds_write_b32 v5, v67 offset:792
	ds_write_b32 v5, v68 offset:1056
	ds_write_b32 v5, v69 offset:1320
	ds_write_b32 v5, v70 offset:1584
	ds_write_b32 v5, v71 offset:1848
	ds_write_b32 v5, v72 offset:2112
	ds_write_b32 v5, v73 offset:2376
	ds_write_b32 v5, v74 offset:2640
	ds_write_b32 v5, v75 offset:2904
	ds_write_b32 v5, v76 offset:3168
	ds_write_b32 v5, v77 offset:3432
	ds_write_b32 v5, v78 offset:3696
	ds_write_b32 v5, v79 offset:3960
	ds_write_b32 v5, v80 offset:4224
	ds_write_b32 v5, v81 offset:4488
	ds_write_b32 v5, v82 offset:4752
	ds_write_b32 v5, v83 offset:5016
	ds_write_b32 v5, v84 offset:5280
	ds_write_b32 v5, v85 offset:5544
	ds_write_b32 v5, v86 offset:5808
	ds_write_b32 v5, v87 offset:6072
	ds_write_b32 v5, v88 offset:6336
	ds_write_b32 v5, v89 offset:6600
	ds_write_b32 v5, v90 offset:6864
	ds_write_b32 v5, v91 offset:7128
	ds_write_b32 v5, v92 offset:7392
	ds_write_b32 v5, v93 offset:7656
	ds_write_b32 v5, v94 offset:7920
	ds_write_b32 v5, v95 offset:8184
	s_bitcmp1_b32 s24, 0
	s_cbranch_scc1 .Lmcv_hg_5
	v_mov_b32_e32 v104, 1.0
	v_mov_b32_e32 v105, 1.0
	v_mov_b32_e32 v106, 1.0
	v_mov_b32_e32 v107, 1.0
	v_mov_b32_e32 v108, 1.0
	v_mov_b32_e32 v109, 1.0
	v_mov_b32_e32 v110, 1.0
	v_mov_b32_e32 v111, 1.0
; __device__ __forceinline__ unsigned cvt_pk_bf16(float lo, float hi) { f32x2_t v = {lo, hi}; bf16x2_t b = __builtin_convertvector(v, bf16x2_t); return __builtin_bit_cast(unsigned, b); }
; #define wt16(p, v) wt16b(WSB, (p), (v))
; #define LAS __attribute__((address_space(3)))
; __device__ __forceinline__ void cvt_store(const unsigned char* WSB, const CvtDesc& d, const float (&wv)[32], LAS float* scr, int lane) {
;     ...
; #pragma unroll
;     for (int j = 0; j < 4; ++j) { const int n = (lane >> 3) + 8 * j; const LAS float* sp = scr + (8 * c) * 33 + n;
;         u32x4 o; o.x = cvt_pk_bf16(sp[0 * 33] * g[0], sp[1 * 33] * g[1]); o.y = cvt_pk_bf16(sp[2 * 33] * g[2], sp[3 * 33] * g[3]);
;         o.z = cvt_pk_bf16(sp[4 * 33] * g[4], sp[5 * 33] * g[5]); o.w = cvt_pk_bf16(sp[6 * 33] * g[6], sp[7 * 33] * g[7]);
;         wt16(d.WT + (size_t)(d.destrow + n) * d.ld + d.k0 + 8 * c, o); }
;     asm volatile("s_waitcnt lgkmcnt(0)" ::: "memory");
; }
; __device__ __forceinline__ void phase_convert(CArgs a, int layer, LAS unsigned char* lds, int G) {
;     ...
; #pragma unroll 1
;         while (it < NIT) {
;             const int nxt = it + NGW;
;             float wn[32]; CvtDesc nd = cur;
;             if (nxt < NIT) { nd = cvt_decode(a, layer, nxt); cvt_load(nd, wn, lane); }
;             cvt_store(WSB, cur, wv, scr, lane);
; #pragma unroll
;             for (int i = 0; i < 32; ++i) wv[i] = wn[i];
;             cur = nd; it = nxt;
;         }
.Lmcv_hg_5:
	v_mad_u32_u24 v11, v8, s26, v9
	s_waitcnt lgkmcnt(0)
	ds_read_b32 v112, v6 offset:0
	ds_read_b32 v113, v6 offset:132
	ds_read_b32 v114, v6 offset:264
	ds_read_b32 v115, v6 offset:396
	ds_read_b32 v116, v6 offset:528
	ds_read_b32 v117, v6 offset:660
	ds_read_b32 v118, v6 offset:792
	ds_read_b32 v119, v6 offset:924
	ds_read_b32 v120, v6 offset:32
	ds_read_b32 v121, v6 offset:164
	ds_read_b32 v122, v6 offset:296
	ds_read_b32 v123, v6 offset:428
	ds_read_b32 v124, v6 offset:560
	ds_read_b32 v125, v6 offset:692
	ds_read_b32 v126, v6 offset:824
	ds_read_b32 v127, v6 offset:956
	ds_read_b32 v128, v6 offset:64
	ds_read_b32 v129, v6 offset:196
	ds_read_b32 v130, v6 offset:328
	ds_read_b32 v131, v6 offset:460
	ds_read_b32 v132, v6 offset:592
	ds_read_b32 v133, v6 offset:724
	ds_read_b32 v134, v6 offset:856
	ds_read_b32 v135, v6 offset:988
	ds_read_b32 v136, v6 offset:96
	ds_read_b32 v137, v6 offset:228
	ds_read_b32 v138, v6 offset:360
	ds_read_b32 v139, v6 offset:492
	ds_read_b32 v140, v6 offset:624
	ds_read_b32 v141, v6 offset:756
	ds_read_b32 v142, v6 offset:888
	ds_read_b32 v143, v6 offset:1020
	s_waitcnt lgkmcnt(0)
	v_mul_f32_e32 v112, v112, v104
	v_mul_f32_e32 v113, v113, v105
	v_mul_f32_e32 v114, v114, v106
	v_mul_f32_e32 v115, v115, v107
	v_mul_f32_e32 v116, v116, v108
	v_mul_f32_e32 v117, v117, v109
	v_mul_f32_e32 v118, v118, v110
	v_mul_f32_e32 v119, v119, v111
	v_mul_f32_e32 v120, v120, v104
	v_mul_f32_e32 v121, v121, v105
	v_mul_f32_e32 v122, v122, v106
	v_mul_f32_e32 v123, v123, v107
	v_mul_f32_e32 v124, v124, v108
	v_mul_f32_e32 v125, v125, v109
	v_mul_f32_e32 v126, v126, v110
	v_mul_f32_e32 v127, v127, v111
	v_mul_f32_e32 v128, v128, v104
	v_mul_f32_e32 v129, v129, v105
	v_mul_f32_e32 v130, v130, v106
	v_mul_f32_e32 v131, v131, v107
	v_mul_f32_e32 v132, v132, v108
	v_mul_f32_e32 v133, v133, v109
	v_mul_f32_e32 v134, v134, v110
	v_mul_f32_e32 v135, v135, v111
	v_mul_f32_e32 v136, v136, v104
	v_mul_f32_e32 v137, v137, v105
	v_mul_f32_e32 v138, v138, v106
	v_mul_f32_e32 v139, v139, v107
	v_mul_f32_e32 v140, v140, v108
	v_mul_f32_e32 v141, v141, v109
	v_mul_f32_e32 v142, v142, v110
	v_mul_f32_e32 v143, v143, v111
	s_bitcmp1_b32 s24, 1
	s_cbranch_scc0 .Lmcv_np_5
	v_mov_b32_e32 v112, 0
	v_mov_b32_e32 v113, 0
	v_mov_b32_e32 v114, 0
	v_mov_b32_e32 v115, 0
	v_mov_b32_e32 v116, 0
	v_mov_b32_e32 v117, 0
	v_mov_b32_e32 v118, 0
	v_mov_b32_e32 v119, 0
	v_mov_b32_e32 v120, 0
	v_mov_b32_e32 v121, 0
	v_mov_b32_e32 v122, 0
	v_mov_b32_e32 v123, 0
	v_mov_b32_e32 v124, 0
	v_mov_b32_e32 v125, 0
	v_mov_b32_e32 v126, 0
	v_mov_b32_e32 v127, 0
	v_mov_b32_e32 v128, 0
	v_mov_b32_e32 v129, 0
	v_mov_b32_e32 v130, 0
	v_mov_b32_e32 v131, 0
	v_mov_b32_e32 v132, 0
	v_mov_b32_e32 v133, 0
	v_mov_b32_e32 v134, 0
	v_mov_b32_e32 v135, 0
	v_mov_b32_e32 v136, 0
	v_mov_b32_e32 v137, 0
	v_mov_b32_e32 v138, 0
	v_mov_b32_e32 v139, 0
	v_mov_b32_e32 v140, 0
	v_mov_b32_e32 v141, 0
	v_mov_b32_e32 v142, 0
	v_mov_b32_e32 v143, 0
.Lmcv_np_5:
	s_lshl_b32 s3, s26, 3
	v_cvt_pk_bf16_f32 v144, v112, v113
	v_cvt_pk_bf16_f32 v145, v114, v115
	v_cvt_pk_bf16_f32 v146, v116, v117
	v_cvt_pk_bf16_f32 v147, v118, v119
	buffer_store_dwordx4 v[144:147], v11, s[88:91], s25 offen sc1
	s_add_u32 s25, s25, s3
	s_nop 0
	v_cvt_pk_bf16_f32 v144, v120, v121
	v_cvt_pk_bf16_f32 v145, v122, v123
	v_cvt_pk_bf16_f32 v146, v124, v125
	v_cvt_pk_bf16_f32 v147, v126, v127
	buffer_store_dwordx4 v[144:147], v11, s[88:91], s25 offen sc1
	s_add_u32 s25, s25, s3
	s_nop 0
	v_cvt_pk_bf16_f32 v144, v128, v129
	v_cvt_pk_bf16_f32 v145, v130, v131
	v_cvt_pk_bf16_f32 v146, v132, v133
	v_cvt_pk_bf16_f32 v147, v134, v135
	buffer_store_dwordx4 v[144:147], v11, s[88:91], s25 offen sc1
	s_add_u32 s25, s25, s3
	s_nop 0
	v_cvt_pk_bf16_f32 v144, v136, v137
	v_cvt_pk_bf16_f32 v145, v138, v139
	v_cvt_pk_bf16_f32 v146, v140, v141
	v_cvt_pk_bf16_f32 v147, v142, v143
	buffer_store_dwordx4 v[144:147], v11, s[88:91], s25 offen sc1
	s_add_u32 s10, s10, s11
	s_cmp_lt_u32 s10, s12
	s_cbranch_scc0 .Lmcv_rd_s
	s_branch .Lmcv_loop_s
.Lmcv_rd_s:
	s_waitcnt vmcnt(0)
.Lmcv_exit:
	s_branch .LBB0_496
.LBB0_557:
	s_endpgm
